# second wave half re-establishes its stagger barrier after next-unit pointer setup and accumulator clearing
# speedup vs baseline: 1.0102x; 1.0102x over previous
; #define PG8_STAGE(bufoff, gbase, voff) do { _Pragma("unroll") for (int _i = 0; _i < 2; ++_i) \
;         __builtin_amdgcn_global_load_lds((const unsigned*)((const char*)(gbase) + (voff)[_i]), (LAS unsigned*)(lds + (bufoff) + ldsw + _i * 8192), 16, 0, 0); } while (0)
; #define PG8_LDA(dst, b, h) do { _Pragma("unroll") for (int m = 0; m < 4; ++m) _Pragma("unroll") for (int k = 0; k < 2; ++k) dst[m][k] = *(const LAS bf16x8*)(lds + PG8_SA(b, h) + aoff + m * 2048 + k * 1024); } while (0)
; #define PG8_LDB(dst, b, h) do { _Pragma("unroll") for (int n = 0; n < 2; ++n) _Pragma("unroll") for (int k = 0; k < 2; ++k) dst[n][k] = *(const LAS bf16x8*)(lds + PG8_SB(b, h) + boff + n * 2048 + k * 1024); } while (0)
; #define PG8_BAR __builtin_amdgcn_s_barrier()
; #define PG8_SCHED __builtin_amdgcn_sched_barrier(0)
; template <class Epi, bool KREV = false>
; __device__ __forceinline__ void gemm_phase(LAS unsigned char* lds, const Gemm g, const StaticOrder& S, const Epi& E, int wave_s) {
;     ...
;         const bool has_next = S.next(ui + 1, nxt);
;         const char* nA = has_next ? (const char*)g.A + (size_t)nxt.pm * tstep + k0off : cA; const char* nB = has_next ? (const char*)g.Bt + (size_t)nxt.pn * bunit + k0off : cB;
;         for (int t = 0; t < nt; t += 2) {
;             const bool last = (t == nt - 2);
;             const char* a1 = cA + (size_t)(t + 1) * kstep;
;             const char* a2 = last ? nA : cA + (size_t)(t + 2) * kstep; const char* b2 = last ? nB : cB + (size_t)(t + 2) * kstep;
;             const char* a3 = a2 + kstep; const char* b3 = b2 + kstep;
;             PG8_LDB(B0, 0, 0); PG8_LDB(B1, 0, 1); PG8_SCHED; PG8_LDA(At, 0, 0); PG8_STAGE(PG8_SA(1, 1), a1 + hstep, voffA);
;     ...
; #pragma unroll
;         for (int a = 0; a < 2; ++a)
; #pragma unroll
;             for (int b = 0; b < 2; ++b)
; #pragma unroll
;                 for (int m = 0; m < 4; ++m)
; #pragma unroll
;                     for (int n = 0; n < 2; ++n) acc[a][b][m][n] = (f32x4){0.f, 0.f, 0.f, 0.f};
;         cur = nxt; cA = nA; cB = nB; ++ui;
;         if (wr == 1) PG8_BAR;
.LBB0_161:
	s_mov_b32 s41, s40
	s_add_i32 s40, s40, 1
	s_mov_b64 s[22:23], s[14:15]
	s_mov_b32 s42, s10
	s_mov_b32 s14, s10
	s_lshl_b32 s10, s40, 5
	s_add_i32 s10, s10, s28
	s_cmp_lt_i32 s10, s1
	s_cselect_b64 s[20:21], -1, 0
	s_ashr_i32 s10, s10, 3
	s_mov_b64 s[24:25], s[12:13]
	s_and_b64 s[12:13], s[20:21], exec
	s_cselect_b32 s12, s10, s14
	s_cselect_b32 s14, s8, s8
	s_ashr_i32 s15, s14, 31
	s_lshl_b64 s[14:15], s[14:15], 20
	s_add_u32 s14, s34, s14
	s_addc_u32 s15, s35, s15
	s_and_b64 s[26:27], s[20:21], exec
	s_cselect_b32 s43, s15, s23
	s_cselect_b32 s44, s14, s22
	s_ashr_i32 s13, s12, 31
	s_lshl_b64 s[12:13], s[12:13], 20
	s_add_u32 s12, s30, s12
	s_addc_u32 s13, s31, s13
	s_and_b64 s[26:27], s[20:21], exec
	s_cselect_b32 s45, s13, s25
	s_cselect_b32 s46, s12, s24
	s_add_u32 s22, s22, 0x80080
	s_addc_u32 s23, s23, 0
	s_add_u32 s47, s24, 0x100
	v_mov_b32_e32 v0, 0
	s_addc_u32 s48, s25, 0
	s_mov_b32 s49, -2
	v_mov_b32_e32 v1, v0
	v_mov_b32_e32 v2, v0
	v_mov_b32_e32 v3, v0
	v_mov_b32_e32 v4, v0
	v_mov_b32_e32 v5, v0
	v_mov_b32_e32 v6, v0
	v_mov_b32_e32 v7, v0
	v_mov_b32_e32 v16, v0
	v_mov_b32_e32 v17, v0
	v_mov_b32_e32 v18, v0
	v_mov_b32_e32 v19, v0
	v_mov_b32_e32 v20, v0
	v_mov_b32_e32 v21, v0
	v_mov_b32_e32 v22, v0
	v_mov_b32_e32 v23, v0
	v_mov_b32_e32 v32, v0
	v_mov_b32_e32 v33, v0
	v_mov_b32_e32 v34, v0
	v_mov_b32_e32 v35, v0
	v_mov_b32_e32 v36, v0
	v_mov_b32_e32 v37, v0
	v_mov_b32_e32 v38, v0
	v_mov_b32_e32 v39, v0
	v_mov_b32_e32 v48, v0
	v_mov_b32_e32 v49, v0
	v_mov_b32_e32 v50, v0
	v_mov_b32_e32 v51, v0
	v_mov_b32_e32 v52, v0
	v_mov_b32_e32 v53, v0
	v_mov_b32_e32 v54, v0
	v_mov_b32_e32 v55, v0
	v_mov_b32_e32 v8, v0
	v_mov_b32_e32 v9, v0
	v_mov_b32_e32 v10, v0
	v_mov_b32_e32 v11, v0
	v_mov_b32_e32 v12, v0
	v_mov_b32_e32 v13, v0
	v_mov_b32_e32 v14, v0
	v_mov_b32_e32 v15, v0
	v_mov_b32_e32 v24, v0
	v_mov_b32_e32 v25, v0
	v_mov_b32_e32 v26, v0
	v_mov_b32_e32 v27, v0
	v_mov_b32_e32 v28, v0
	v_mov_b32_e32 v29, v0
	v_mov_b32_e32 v30, v0
	v_mov_b32_e32 v31, v0
	v_mov_b32_e32 v40, v0
	v_mov_b32_e32 v41, v0
	v_mov_b32_e32 v42, v0
	v_mov_b32_e32 v43, v0
	v_mov_b32_e32 v44, v0
	v_mov_b32_e32 v45, v0
	v_mov_b32_e32 v46, v0
	v_mov_b32_e32 v47, v0
	v_mov_b32_e32 v56, v0
	v_mov_b32_e32 v57, v0
	v_mov_b32_e32 v58, v0
	v_mov_b32_e32 v59, v0
	v_mov_b32_e32 v60, v0
	v_mov_b32_e32 v61, v0
	v_mov_b32_e32 v62, v0
	v_mov_b32_e32 v63, v0
	v_mov_b32_e32 v64, v0
	v_mov_b32_e32 v65, v0
	v_mov_b32_e32 v66, v0
	v_mov_b32_e32 v67, v0
	v_mov_b32_e32 v68, v0
	v_mov_b32_e32 v69, v0
	v_mov_b32_e32 v70, v0
	v_mov_b32_e32 v71, v0
	v_mov_b32_e32 v80, v0
	v_mov_b32_e32 v81, v0
	v_mov_b32_e32 v82, v0
	v_mov_b32_e32 v83, v0
	v_mov_b32_e32 v84, v0
	v_mov_b32_e32 v85, v0
	v_mov_b32_e32 v86, v0
	v_mov_b32_e32 v87, v0
	v_mov_b32_e32 v96, v0
	v_mov_b32_e32 v97, v0
	v_mov_b32_e32 v98, v0
	v_mov_b32_e32 v99, v0
	v_mov_b32_e32 v100, v0
	v_mov_b32_e32 v101, v0
	v_mov_b32_e32 v102, v0
	v_mov_b32_e32 v103, v0
	v_mov_b32_e32 v112, v0
	v_mov_b32_e32 v113, v0
	v_mov_b32_e32 v114, v0
	v_mov_b32_e32 v115, v0
	v_mov_b32_e32 v116, v0
	v_mov_b32_e32 v117, v0
	v_mov_b32_e32 v118, v0
	v_mov_b32_e32 v119, v0
	v_mov_b32_e32 v72, v0
	v_mov_b32_e32 v73, v0
	v_mov_b32_e32 v74, v0
	v_mov_b32_e32 v75, v0
	v_mov_b32_e32 v76, v0
	v_mov_b32_e32 v77, v0
	v_mov_b32_e32 v78, v0
	v_mov_b32_e32 v79, v0
	v_mov_b32_e32 v88, v0
	v_mov_b32_e32 v89, v0
	v_mov_b32_e32 v90, v0
	v_mov_b32_e32 v91, v0
	v_mov_b32_e32 v92, v0
	v_mov_b32_e32 v93, v0
	v_mov_b32_e32 v94, v0
	v_mov_b32_e32 v95, v0
	v_mov_b32_e32 v104, v0
	v_mov_b32_e32 v105, v0
	v_mov_b32_e32 v106, v0
	v_mov_b32_e32 v107, v0
	v_mov_b32_e32 v108, v0
	v_mov_b32_e32 v109, v0
	v_mov_b32_e32 v110, v0
	v_mov_b32_e32 v111, v0
	v_mov_b32_e32 v120, v0
	v_mov_b32_e32 v121, v0
	v_mov_b32_e32 v122, v0
	v_mov_b32_e32 v123, v0
	v_mov_b32_e32 v124, v0
	v_mov_b32_e32 v125, v0
	v_mov_b32_e32 v126, v0
	v_mov_b32_e32 v127, v0
	s_cmp_eq_u32 s41, 0
	s_cbranch_scc1 .Lsb0
	s_andn2_b64 vcc, exec, s[16:17]
	s_cbranch_vccnz .Lsb0
	s_barrier
.Lsb0:
.LBB0_162:
	v_add_u32_e32 v138, 0x10000, v140
	ds_read_b128 v[146:149], v138
	ds_read_b128 v[150:153], v138 offset:1024
	ds_read_b128 v[154:157], v138 offset:2048
	ds_read_b128 v[158:161], v138 offset:3072
	v_add_u32_e32 v138, 0x14000, v140
	ds_read_b128 v[162:165], v138
	ds_read_b128 v[166:169], v138 offset:1024
	ds_read_b128 v[170:173], v138 offset:2048
	ds_read_b128 v[178:181], v138 offset:3072
	ds_read_b128 v[182:185], v143
	ds_read_b128 v[186:189], v143 offset:1024
	ds_read_b128 v[190:193], v143 offset:2048
	ds_read_b128 v[194:197], v143 offset:3072
	ds_read_b128 v[198:201], v143 offset:4096
	ds_read_b128 v[202:205], v143 offset:5120
	ds_read_b128 v[218:221], v143 offset:6144
	ds_read_b128 v[222:225], v143 offset:7168
	s_add_u32 s24, s22, 0xfff80080
	s_addc_u32 s25, s23, -1
	s_add_i32 s50, 0, 0x10000
	s_cmp_eq_u32 s49, 28
	s_cselect_b32 s27, s43, s25
	s_cselect_b32 s26, s44, s24
	s_cselect_b32 s25, s45, s48
	s_cselect_b32 s24, s46, s47
	s_add_i32 s52, 0, 0x14000
	s_add_i32 m0, s9, 0xc000
	s_nop 0
	global_load_lds_dwordx4 v134, s[22:23]
	s_add_i32 m0, s9, 0xe000
	s_nop 0
	global_load_lds_dwordx4 v136, s[22:23]
	s_waitcnt vmcnt(8)
	s_waitcnt lgkmcnt(0)
	s_barrier
; #define PG8_STAGE(bufoff, gbase, voff) do { _Pragma("unroll") for (int _i = 0; _i < 2; ++_i) \
;         __builtin_amdgcn_global_load_lds((const unsigned*)((const char*)(gbase) + (voff)[_i]), (LAS unsigned*)(lds + (bufoff) + ldsw + _i * 8192), 16, 0, 0); } while (0)
; #define PG8_LDA(dst, b, h) do { _Pragma("unroll") for (int m = 0; m < 4; ++m) _Pragma("unroll") for (int k = 0; k < 2; ++k) dst[m][k] = *(const LAS bf16x8*)(lds + PG8_SA(b, h) + aoff + m * 2048 + k * 1024); } while (0)
; #define PG8_MMA(ai, bj, At, Bt) do { __builtin_amdgcn_s_setprio(1); _Pragma("unroll") for (int m = 0; m < 4; ++m) _Pragma("unroll") for (int n = 0; n < 2; ++n) _Pragma("unroll") for (int k = 0; k < 2; ++k) \
;         acc[ai][bj][m][n] = __builtin_amdgcn_mfma_f32_16x16x32_bf16(Bt[n][k], At[m][k], acc[ai][bj][m][n], 0, 0, 0); __builtin_amdgcn_s_setprio(0); } while (0)
; #define PG8_WAIT_V(n) asm volatile("s_waitcnt vmcnt(" #n ")" ::: "memory")
; #define PG8_WAIT_L(n) asm volatile("s_waitcnt lgkmcnt(" #n ")" ::: "memory")
; #define PG8_BAR __builtin_amdgcn_s_barrier()
; #define PG8_SCHED __builtin_amdgcn_sched_barrier(0)
; template <class Epi, bool KREV = false>
; __device__ __forceinline__ void gemm_phase(LAS unsigned char* lds, const Gemm g, const StaticOrder& S, const Epi& E, int wave_s) {
;     ...
;             PG8_WAIT_V(8); PG8_WAIT_L(0); PG8_BAR; PG8_MMA(0, 0, At, B0); PG8_MMA(0, 1, At, B1); PG8_BAR; PG8_SCHED;
;             PG8_LDA(At, 0, 1); PG8_STAGE(PG8_SB(0, 0), b2, voffB); PG8_STAGE(PG8_SB(0, 1), b2 + bh, voffB); PG8_STAGE(PG8_SA(0, 0), a2, voffA);
;             PG8_WAIT_V(8); PG8_WAIT_L(0); PG8_BAR; PG8_MMA(1, 0, At, B0); PG8_MMA(1, 1, At, B1); PG8_BAR; PG8_SCHED;
	s_setprio 1
	s_waitcnt lgkmcnt(0)
	v_mfma_f32_16x16x32_bf16 v[124:127], v[146:149], v[182:185], v[124:127]
	v_mfma_f32_16x16x32_bf16 v[120:123], v[154:157], v[182:185], v[120:123]
	v_mfma_f32_16x16x32_bf16 v[108:111], v[146:149], v[190:193], v[108:111]
	v_mfma_f32_16x16x32_bf16 v[104:107], v[154:157], v[190:193], v[104:107]
	v_mfma_f32_16x16x32_bf16 v[92:95], v[146:149], v[198:201], v[92:95]
	v_mfma_f32_16x16x32_bf16 v[88:91], v[154:157], v[198:201], v[88:91]
	v_mfma_f32_16x16x32_bf16 v[76:79], v[146:149], v[218:221], v[76:79]
	v_mfma_f32_16x16x32_bf16 v[72:75], v[154:157], v[218:221], v[72:75]
	v_mfma_f32_16x16x32_bf16 v[124:127], v[150:153], v[186:189], v[124:127]
	v_mfma_f32_16x16x32_bf16 v[120:123], v[158:161], v[186:189], v[120:123]
	v_mfma_f32_16x16x32_bf16 v[108:111], v[150:153], v[194:197], v[108:111]
	v_mfma_f32_16x16x32_bf16 v[104:107], v[158:161], v[194:197], v[104:107]
	v_mfma_f32_16x16x32_bf16 v[92:95], v[150:153], v[202:205], v[92:95]
	v_mfma_f32_16x16x32_bf16 v[88:91], v[158:161], v[202:205], v[88:91]
	v_mfma_f32_16x16x32_bf16 v[76:79], v[150:153], v[222:225], v[76:79]
	v_mfma_f32_16x16x32_bf16 v[72:75], v[158:161], v[222:225], v[72:75]
	s_setprio 0
	s_setprio 1
	v_mfma_f32_16x16x32_bf16 v[116:119], v[162:165], v[182:185], v[116:119]
	v_mfma_f32_16x16x32_bf16 v[112:115], v[170:173], v[182:185], v[112:115]
	v_mfma_f32_16x16x32_bf16 v[100:103], v[162:165], v[190:193], v[100:103]
	v_mfma_f32_16x16x32_bf16 v[96:99], v[170:173], v[190:193], v[96:99]
	v_mfma_f32_16x16x32_bf16 v[84:87], v[162:165], v[198:201], v[84:87]
	v_mfma_f32_16x16x32_bf16 v[80:83], v[170:173], v[198:201], v[80:83]
	v_mfma_f32_16x16x32_bf16 v[68:71], v[162:165], v[218:221], v[68:71]
	v_mfma_f32_16x16x32_bf16 v[64:67], v[170:173], v[218:221], v[64:67]
	v_mfma_f32_16x16x32_bf16 v[116:119], v[166:169], v[186:189], v[116:119]
	v_mfma_f32_16x16x32_bf16 v[112:115], v[178:181], v[186:189], v[112:115]
	v_mfma_f32_16x16x32_bf16 v[100:103], v[166:169], v[194:197], v[100:103]
	v_mfma_f32_16x16x32_bf16 v[96:99], v[178:181], v[194:197], v[96:99]
	v_mfma_f32_16x16x32_bf16 v[84:87], v[166:169], v[202:205], v[84:87]
	v_mfma_f32_16x16x32_bf16 v[80:83], v[178:181], v[202:205], v[80:83]
	v_mfma_f32_16x16x32_bf16 v[68:71], v[166:169], v[222:225], v[68:71]
	s_barrier
	v_mfma_f32_16x16x32_bf16 v[64:67], v[178:181], v[222:225], v[64:67]
	s_setprio 0
	s_add_u32 s98, s24, s2
	s_addc_u32 s99, s25, s3
	s_add_u32 s100, s26, s2
	s_addc_u32 s101, s27, s3
	s_add_i32 s50, s50, s29
	s_mov_b32 m0, s50
	ds_read_b128 v[182:185], v143 offset:16384
	ds_read_b128 v[186:189], v143 offset:17408
	ds_read_b128 v[190:193], v143 offset:18432
	ds_read_b128 v[194:197], v143 offset:19456
	ds_read_b128 v[198:201], v143 offset:20480
	ds_read_b128 v[202:205], v143 offset:21504
	ds_read_b128 v[218:221], v143 offset:22528
	ds_read_b128 v[222:225], v143 offset:23552
	global_load_lds_dwordx4 v176, s[24:25]
	s_add_i32 m0, s50, 0x2000
	s_add_u32 s50, s24, 0x80000
	s_addc_u32 s51, s25, 0
	s_add_i32 s52, s52, s29
	global_load_lds_dwordx4 v132, s[24:25]
	s_mov_b32 m0, s52
	v_lshl_add_u64 v[226:227], s[26:27], 0, v[130:131]
	global_load_lds_dwordx4 v176, s[50:51]
	s_add_i32 m0, s52, 0x2000
	s_nop 0
	global_load_lds_dwordx4 v132, s[50:51]
	s_mov_b32 m0, s9
	s_nop 0
	global_load_lds_dwordx4 v128, s[26:27]
	s_mov_b32 m0, s11
	s_nop 0
	global_load_lds_dwordx4 v130, s[26:27]
	s_waitcnt vmcnt(8)
	s_waitcnt lgkmcnt(0)
	s_barrier
	s_setprio 1
	s_waitcnt lgkmcnt(0)
	v_mfma_f32_16x16x32_bf16 v[60:63], v[146:149], v[182:185], v[60:63]
	v_mfma_f32_16x16x32_bf16 v[56:59], v[154:157], v[182:185], v[56:59]
	v_mfma_f32_16x16x32_bf16 v[44:47], v[146:149], v[190:193], v[44:47]
	v_mfma_f32_16x16x32_bf16 v[40:43], v[154:157], v[190:193], v[40:43]
	v_mfma_f32_16x16x32_bf16 v[28:31], v[146:149], v[198:201], v[28:31]
	v_mfma_f32_16x16x32_bf16 v[24:27], v[154:157], v[198:201], v[24:27]
	v_mfma_f32_16x16x32_bf16 v[12:15], v[146:149], v[218:221], v[12:15]
	v_mfma_f32_16x16x32_bf16 v[8:11], v[154:157], v[218:221], v[8:11]
	v_mfma_f32_16x16x32_bf16 v[60:63], v[150:153], v[186:189], v[60:63]
	v_mfma_f32_16x16x32_bf16 v[56:59], v[158:161], v[186:189], v[56:59]
	v_mfma_f32_16x16x32_bf16 v[44:47], v[150:153], v[194:197], v[44:47]
	v_mfma_f32_16x16x32_bf16 v[40:43], v[158:161], v[194:197], v[40:43]
	v_mfma_f32_16x16x32_bf16 v[28:31], v[150:153], v[202:205], v[28:31]
	v_mfma_f32_16x16x32_bf16 v[24:27], v[158:161], v[202:205], v[24:27]
	v_mfma_f32_16x16x32_bf16 v[12:15], v[150:153], v[222:225], v[12:15]
	v_mfma_f32_16x16x32_bf16 v[8:11], v[158:161], v[222:225], v[8:11]
	s_setprio 0
	s_setprio 1
	v_mfma_f32_16x16x32_bf16 v[52:55], v[162:165], v[182:185], v[52:55]
	v_mfma_f32_16x16x32_bf16 v[48:51], v[170:173], v[182:185], v[48:51]
	v_mfma_f32_16x16x32_bf16 v[36:39], v[162:165], v[190:193], v[36:39]
	v_mfma_f32_16x16x32_bf16 v[32:35], v[170:173], v[190:193], v[32:35]
	v_mfma_f32_16x16x32_bf16 v[20:23], v[162:165], v[198:201], v[20:23]
	v_mfma_f32_16x16x32_bf16 v[16:19], v[170:173], v[198:201], v[16:19]
	v_mfma_f32_16x16x32_bf16 v[4:7], v[162:165], v[218:221], v[4:7]
	v_mfma_f32_16x16x32_bf16 v[0:3], v[170:173], v[218:221], v[0:3]
	v_mfma_f32_16x16x32_bf16 v[52:55], v[166:169], v[186:189], v[52:55]
	v_mfma_f32_16x16x32_bf16 v[48:51], v[178:181], v[186:189], v[48:51]
	v_mfma_f32_16x16x32_bf16 v[36:39], v[166:169], v[194:197], v[36:39]
	v_mfma_f32_16x16x32_bf16 v[32:35], v[178:181], v[194:197], v[32:35]
	v_mfma_f32_16x16x32_bf16 v[20:23], v[166:169], v[202:205], v[20:23]
	v_mfma_f32_16x16x32_bf16 v[16:19], v[178:181], v[202:205], v[16:19]
	v_mfma_f32_16x16x32_bf16 v[4:7], v[166:169], v[222:225], v[4:7]
	s_barrier
; #define PG8_STAGE(bufoff, gbase, voff) do { _Pragma("unroll") for (int _i = 0; _i < 2; ++_i) \
;         __builtin_amdgcn_global_load_lds((const unsigned*)((const char*)(gbase) + (voff)[_i]), (LAS unsigned*)(lds + (bufoff) + ldsw + _i * 8192), 16, 0, 0); } while (0)
; #define PG8_LDA(dst, b, h) do { _Pragma("unroll") for (int m = 0; m < 4; ++m) _Pragma("unroll") for (int k = 0; k < 2; ++k) dst[m][k] = *(const LAS bf16x8*)(lds + PG8_SA(b, h) + aoff + m * 2048 + k * 1024); } while (0)
; #define PG8_LDB(dst, b, h) do { _Pragma("unroll") for (int n = 0; n < 2; ++n) _Pragma("unroll") for (int k = 0; k < 2; ++k) dst[n][k] = *(const LAS bf16x8*)(lds + PG8_SB(b, h) + boff + n * 2048 + k * 1024); } while (0)
; #define PG8_MMA(ai, bj, At, Bt) do { __builtin_amdgcn_s_setprio(1); _Pragma("unroll") for (int m = 0; m < 4; ++m) _Pragma("unroll") for (int n = 0; n < 2; ++n) _Pragma("unroll") for (int k = 0; k < 2; ++k) \
;         acc[ai][bj][m][n] = __builtin_amdgcn_mfma_f32_16x16x32_bf16(Bt[n][k], At[m][k], acc[ai][bj][m][n], 0, 0, 0); __builtin_amdgcn_s_setprio(0); } while (0)
; #define PG8_WAIT_V(n) asm volatile("s_waitcnt vmcnt(" #n ")" ::: "memory")
; #define PG8_WAIT_L(n) asm volatile("s_waitcnt lgkmcnt(" #n ")" ::: "memory")
; #define PG8_BAR __builtin_amdgcn_s_barrier()
; #define PG8_SCHED __builtin_amdgcn_sched_barrier(0)
; template <class Epi, bool KREV = false>
; __device__ __forceinline__ void gemm_phase(LAS unsigned char* lds, const Gemm g, const StaticOrder& S, const Epi& E, int wave_s) {
;     ...
;             PG8_LDB(B0, 1, 0); PG8_LDB(B1, 1, 1); PG8_SCHED; PG8_LDA(At, 1, 0); PG8_STAGE(PG8_SA(0, 1), a2 + hstep, voffA);
;             PG8_WAIT_V(8); PG8_WAIT_L(0); PG8_BAR; PG8_MMA(0, 0, At, B0); PG8_MMA(0, 1, At, B1); PG8_BAR; PG8_SCHED;
;             PG8_LDA(At, 1, 1); PG8_STAGE(PG8_SB(1, 0), b3, voffB); PG8_STAGE(PG8_SB(1, 1), b3 + bh, voffB); PG8_STAGE(PG8_SA(1, 0), a3, voffA);
;             PG8_WAIT_V(8); PG8_WAIT_L(0); PG8_BAR; PG8_MMA(1, 0, At, B0); PG8_MMA(1, 1, At, B1); PG8_BAR; PG8_SCHED;
;         }
;         if (wr == 0) PG8_BAR;
	v_mfma_f32_16x16x32_bf16 v[0:3], v[178:181], v[222:225], v[0:3]
	s_setprio 0
	s_add_i32 s50, 0, 0x18000
	v_add_u32_e32 v145, s50, v140
	s_add_i32 s51, 0, 0x1c000
	ds_read_b128 v[146:149], v145
	ds_read_b128 v[150:153], v145 offset:1024
	ds_read_b128 v[154:157], v145 offset:2048
	ds_read_b128 v[158:161], v145 offset:3072
	v_add_u32_e32 v145, s51, v140
	ds_read_b128 v[162:165], v145
	ds_read_b128 v[166:169], v145 offset:1024
	ds_read_b128 v[170:173], v145 offset:2048
	ds_read_b128 v[178:181], v145 offset:3072
	s_add_u32 s26, s26, 0x80000
	s_addc_u32 s27, s27, 0
	s_mov_b32 m0, s36
	ds_read_b128 v[182:185], v143 offset:32768
	ds_read_b128 v[186:189], v143 offset:33792
	ds_read_b128 v[190:193], v143 offset:34816
	ds_read_b128 v[194:197], v143 offset:35840
	ds_read_b128 v[198:201], v143 offset:36864
	ds_read_b128 v[202:205], v143 offset:37888
	ds_read_b128 v[218:221], v143 offset:38912
	ds_read_b128 v[222:225], v143 offset:39936
	global_load_lds_dwordx4 v128, s[26:27]
	s_mov_b32 m0, s37
	s_nop 0
	global_load_lds_dwordx4 v130, s[26:27]
	s_waitcnt vmcnt(8)
	s_waitcnt lgkmcnt(0)
	s_barrier
	s_setprio 1
	s_waitcnt lgkmcnt(0)
	v_mfma_f32_16x16x32_bf16 v[124:127], v[146:149], v[182:185], v[124:127]
	v_mfma_f32_16x16x32_bf16 v[120:123], v[154:157], v[182:185], v[120:123]
	v_mfma_f32_16x16x32_bf16 v[108:111], v[146:149], v[190:193], v[108:111]
	v_mfma_f32_16x16x32_bf16 v[104:107], v[154:157], v[190:193], v[104:107]
	v_mfma_f32_16x16x32_bf16 v[92:95], v[146:149], v[198:201], v[92:95]
	v_mfma_f32_16x16x32_bf16 v[88:91], v[154:157], v[198:201], v[88:91]
	v_mfma_f32_16x16x32_bf16 v[76:79], v[146:149], v[218:221], v[76:79]
	v_mfma_f32_16x16x32_bf16 v[72:75], v[154:157], v[218:221], v[72:75]
	v_mfma_f32_16x16x32_bf16 v[124:127], v[150:153], v[186:189], v[124:127]
	v_mfma_f32_16x16x32_bf16 v[120:123], v[158:161], v[186:189], v[120:123]
	v_mfma_f32_16x16x32_bf16 v[108:111], v[150:153], v[194:197], v[108:111]
	v_mfma_f32_16x16x32_bf16 v[104:107], v[158:161], v[194:197], v[104:107]
	v_mfma_f32_16x16x32_bf16 v[92:95], v[150:153], v[202:205], v[92:95]
	v_mfma_f32_16x16x32_bf16 v[88:91], v[158:161], v[202:205], v[88:91]
	v_mfma_f32_16x16x32_bf16 v[76:79], v[150:153], v[222:225], v[76:79]
	v_mfma_f32_16x16x32_bf16 v[72:75], v[158:161], v[222:225], v[72:75]
	s_setprio 0
	s_setprio 1
	v_mfma_f32_16x16x32_bf16 v[116:119], v[162:165], v[182:185], v[116:119]
	v_mfma_f32_16x16x32_bf16 v[112:115], v[170:173], v[182:185], v[112:115]
	v_mfma_f32_16x16x32_bf16 v[100:103], v[162:165], v[190:193], v[100:103]
	v_mfma_f32_16x16x32_bf16 v[96:99], v[170:173], v[190:193], v[96:99]
	v_mfma_f32_16x16x32_bf16 v[84:87], v[162:165], v[198:201], v[84:87]
	v_mfma_f32_16x16x32_bf16 v[80:83], v[170:173], v[198:201], v[80:83]
	v_mfma_f32_16x16x32_bf16 v[68:71], v[162:165], v[218:221], v[68:71]
	v_mfma_f32_16x16x32_bf16 v[64:67], v[170:173], v[218:221], v[64:67]
	v_mfma_f32_16x16x32_bf16 v[116:119], v[166:169], v[186:189], v[116:119]
	v_mfma_f32_16x16x32_bf16 v[112:115], v[178:181], v[186:189], v[112:115]
	v_mfma_f32_16x16x32_bf16 v[100:103], v[166:169], v[194:197], v[100:103]
	v_mfma_f32_16x16x32_bf16 v[96:99], v[178:181], v[194:197], v[96:99]
	v_mfma_f32_16x16x32_bf16 v[84:87], v[166:169], v[202:205], v[84:87]
	v_mfma_f32_16x16x32_bf16 v[80:83], v[178:181], v[202:205], v[80:83]
	v_mfma_f32_16x16x32_bf16 v[68:71], v[166:169], v[222:225], v[68:71]
	s_barrier
	v_mfma_f32_16x16x32_bf16 v[64:67], v[178:181], v[222:225], v[64:67]
	s_setprio 0
	s_add_i32 s26, s50, s29
	s_mov_b32 m0, s26
	ds_read_b128 v[182:185], v143 offset:49152
	ds_read_b128 v[186:189], v143 offset:50176
	ds_read_b128 v[190:193], v143 offset:51200
	ds_read_b128 v[194:197], v143 offset:52224
	ds_read_b128 v[198:201], v143 offset:53248
	ds_read_b128 v[202:205], v143 offset:54272
	ds_read_b128 v[218:221], v143 offset:55296
	ds_read_b128 v[222:225], v143 offset:56320
	global_load_lds_dwordx4 v176, s[98:99]
	s_add_i32 m0, s26, 0x2000
	s_add_u32 s24, s24, 0x80080
	s_addc_u32 s25, s25, 0
	s_add_i32 s26, s51, s29
	global_load_lds_dwordx4 v132, s[98:99]
	s_mov_b32 m0, s26
	s_nop 0
	global_load_lds_dwordx4 v176, s[24:25]
	s_add_i32 m0, s26, 0x2000
	s_nop 0
	global_load_lds_dwordx4 v132, s[24:25]
	s_mov_b32 m0, s38
	s_nop 0
	global_load_lds_dwordx4 v128, s[100:101]
	v_lshl_add_u64 v[138:139], v[226:227], 0, s[2:3]
	s_mov_b32 m0, s39
	s_nop 0
	global_load_lds_dwordx4 v130, s[100:101]
	s_waitcnt vmcnt(8)
	s_waitcnt lgkmcnt(0)
	s_barrier
	s_setprio 1
	s_waitcnt lgkmcnt(0)
	v_mfma_f32_16x16x32_bf16 v[60:63], v[146:149], v[182:185], v[60:63]
	v_mfma_f32_16x16x32_bf16 v[56:59], v[154:157], v[182:185], v[56:59]
	v_mfma_f32_16x16x32_bf16 v[44:47], v[146:149], v[190:193], v[44:47]
	v_mfma_f32_16x16x32_bf16 v[40:43], v[154:157], v[190:193], v[40:43]
	v_mfma_f32_16x16x32_bf16 v[28:31], v[146:149], v[198:201], v[28:31]
	v_mfma_f32_16x16x32_bf16 v[24:27], v[154:157], v[198:201], v[24:27]
	v_mfma_f32_16x16x32_bf16 v[12:15], v[146:149], v[218:221], v[12:15]
	v_mfma_f32_16x16x32_bf16 v[8:11], v[154:157], v[218:221], v[8:11]
	v_mfma_f32_16x16x32_bf16 v[60:63], v[150:153], v[186:189], v[60:63]
	v_mfma_f32_16x16x32_bf16 v[56:59], v[158:161], v[186:189], v[56:59]
	v_mfma_f32_16x16x32_bf16 v[44:47], v[150:153], v[194:197], v[44:47]
	v_mfma_f32_16x16x32_bf16 v[40:43], v[158:161], v[194:197], v[40:43]
	v_mfma_f32_16x16x32_bf16 v[28:31], v[150:153], v[202:205], v[28:31]
	v_mfma_f32_16x16x32_bf16 v[24:27], v[158:161], v[202:205], v[24:27]
	v_mfma_f32_16x16x32_bf16 v[12:15], v[150:153], v[222:225], v[12:15]
	v_mfma_f32_16x16x32_bf16 v[8:11], v[158:161], v[222:225], v[8:11]
	s_setprio 0
	s_setprio 1
	v_mfma_f32_16x16x32_bf16 v[52:55], v[162:165], v[182:185], v[52:55]
	v_mfma_f32_16x16x32_bf16 v[48:51], v[170:173], v[182:185], v[48:51]
	v_mfma_f32_16x16x32_bf16 v[36:39], v[162:165], v[190:193], v[36:39]
	v_mfma_f32_16x16x32_bf16 v[32:35], v[170:173], v[190:193], v[32:35]
	v_mfma_f32_16x16x32_bf16 v[20:23], v[162:165], v[198:201], v[20:23]
	v_mfma_f32_16x16x32_bf16 v[16:19], v[170:173], v[198:201], v[16:19]
	v_mfma_f32_16x16x32_bf16 v[4:7], v[162:165], v[218:221], v[4:7]
	v_mfma_f32_16x16x32_bf16 v[0:3], v[170:173], v[218:221], v[0:3]
	v_mfma_f32_16x16x32_bf16 v[52:55], v[166:169], v[186:189], v[52:55]
	v_mfma_f32_16x16x32_bf16 v[48:51], v[178:181], v[186:189], v[48:51]
	v_mfma_f32_16x16x32_bf16 v[36:39], v[166:169], v[194:197], v[36:39]
	v_mfma_f32_16x16x32_bf16 v[32:35], v[178:181], v[194:197], v[32:35]
	s_add_i32 s49, s49, 2
	s_add_u32 s22, s22, 0x100
	s_addc_u32 s23, s23, 0
	v_mfma_f32_16x16x32_bf16 v[20:23], v[166:169], v[202:205], v[20:23]
	s_add_u32 s47, s47, 0x100
	s_addc_u32 s48, s48, 0
	v_mfma_f32_16x16x32_bf16 v[16:19], v[178:181], v[202:205], v[16:19]
	s_cmp_gt_u32 s49, 29
	v_mfma_f32_16x16x32_bf16 v[4:7], v[166:169], v[222:225], v[4:7]
	s_barrier
	v_mfma_f32_16x16x32_bf16 v[0:3], v[178:181], v[222:225], v[0:3]
	s_setprio 0
	s_cbranch_scc0 .LBB0_162
	s_and_b64 vcc, exec, s[18:19]
	s_cbranch_vccz .LBB0_165
	s_barrier
; #define LAS __attribute__((address_space(3)))
; __device__ __forceinline__ unsigned cvt_pk_bf16(float lo, float hi) { unsigned r; asm volatile("v_cvt_pk_bf16_f32 %0, %1, %2" : "=v"(r) : "v"(lo), "v"(hi)); return r; }
;     __device__ __forceinline__ void operator()(f32x4 (&acc)[2][2][4][2], const Unit& u, int wr, int wc, int fr, int fq, const LAS float* rtab) const {
;         const int row0 = u.pm * BM + wr * 64 + fr, col0 = u.pn * BM + wc * 32 + 8 * fq;
; #pragma unroll
;         for (int ai = 0; ai < 2; ++ai)
; #pragma unroll
;             for (int m = 0; m < 4; ++m) { bf16_t* rowp = O + (size_t)(row0 + ai * HALF + m * 16) * ldc + col0; const float r = rtab[ai * HALF + wr * 64 + m * 16 + fr];
; #pragma unroll
;                 for (int bj = 0; bj < 2; ++bj) { const f32x4 v0 = acc[ai][bj][m][0] * r, v1 = acc[ai][bj][m][1] * r;
;                     u32x4 w; w.x = cvt_pk_bf16(v0[0], v0[1]); w.y = cvt_pk_bf16(v0[2], v0[3]); w.z = cvt_pk_bf16(v1[0], v1[1]); w.w = cvt_pk_bf16(v1[2], v1[3]);
;                     *(u32x4*)(rowp + bj * HALF) = w; } }
;     }
.LBB0_165:
	v_lshl_add_u32 v145, s41, 10, v141
	ds_read_b32 v146, v145
	v_lshl_or_b32 v138, s42, 8, v142
	v_ashrrev_i32_e32 v139, 31, v138
	v_mad_i64_i32 v[148:149], s[22:23], v144, s0, 0
	v_lshl_add_u64 v[148:149], v[148:149], 1, s[6:7]
	v_lshlrev_b64 v[138:139], 1, v[138:139]
	v_lshl_add_u64 v[148:149], v[148:149], 0, v[138:139]
	s_waitcnt lgkmcnt(0)
	v_pk_mul_f32 v[126:127], v[126:127], v[146:147] op_sel_hi:[1,0]
	v_pk_mul_f32 v[124:125], v[124:125], v[146:147] op_sel_hi:[1,0]
	v_pk_mul_f32 v[150:151], v[122:123], v[146:147] op_sel_hi:[1,0]
	v_pk_mul_f32 v[122:123], v[120:121], v[146:147] op_sel_hi:[1,0]
	v_cvt_pk_bf16_f32 v120, v124, v125
	v_cvt_pk_bf16_f32 v121, v126, v127
	v_pk_mul_f32 v[116:117], v[116:117], v[146:147] op_sel_hi:[1,0]
	v_cvt_pk_bf16_f32 v122, v122, v123
	v_cvt_pk_bf16_f32 v123, v150, v151
	global_store_dwordx4 v[148:149], v[120:123], off
	v_pk_mul_f32 v[118:119], v[118:119], v[146:147] op_sel_hi:[1,0]
	s_andn2_b64 vcc, exec, s[20:21]
	v_pk_mul_f32 v[120:121], v[114:115], v[146:147] op_sel_hi:[1,0]
	v_pk_mul_f32 v[114:115], v[112:113], v[146:147] op_sel_hi:[1,0]
	v_cvt_pk_bf16_f32 v112, v116, v117
	v_cvt_pk_bf16_f32 v113, v118, v119
	s_mov_b64 s[20:21], -1
	v_cvt_pk_bf16_f32 v114, v114, v115
	v_cvt_pk_bf16_f32 v115, v120, v121
	global_store_dwordx4 v[148:149], v[112:115], off offset:256
	ds_read_b32 v112, v145 offset:64
	s_nop 0
	v_or_b32_e32 v113, 16, v144
	v_mad_i64_i32 v[114:115], s[22:23], v113, s0, 0
	v_lshl_add_u64 v[114:115], v[114:115], 1, s[6:7]
	v_lshl_add_u64 v[114:115], v[114:115], 0, v[138:139]
	s_waitcnt lgkmcnt(0)
	v_pk_mul_f32 v[110:111], v[110:111], v[112:113] op_sel_hi:[1,0]
	v_pk_mul_f32 v[108:109], v[108:109], v[112:113] op_sel_hi:[1,0]
	v_pk_mul_f32 v[116:117], v[106:107], v[112:113] op_sel_hi:[1,0]
	v_pk_mul_f32 v[106:107], v[104:105], v[112:113] op_sel_hi:[1,0]
	v_cvt_pk_bf16_f32 v104, v108, v109
	v_cvt_pk_bf16_f32 v105, v110, v111
	v_pk_mul_f32 v[100:101], v[100:101], v[112:113] op_sel_hi:[1,0]
	v_cvt_pk_bf16_f32 v106, v106, v107
	v_cvt_pk_bf16_f32 v107, v116, v117
	global_store_dwordx4 v[114:115], v[104:107], off
	v_pk_mul_f32 v[102:103], v[102:103], v[112:113] op_sel_hi:[1,0]
	s_nop 0
	v_pk_mul_f32 v[104:105], v[98:99], v[112:113] op_sel_hi:[1,0]
	v_pk_mul_f32 v[98:99], v[96:97], v[112:113] op_sel_hi:[1,0]
	v_cvt_pk_bf16_f32 v96, v100, v101
	v_cvt_pk_bf16_f32 v97, v102, v103
	s_nop 0
	v_cvt_pk_bf16_f32 v98, v98, v99
	v_cvt_pk_bf16_f32 v99, v104, v105
	global_store_dwordx4 v[114:115], v[96:99], off offset:256
	ds_read_b32 v96, v145 offset:128
	s_nop 0
	v_or_b32_e32 v97, 32, v144
	v_mad_i64_i32 v[98:99], s[22:23], v97, s0, 0
	v_lshl_add_u64 v[98:99], v[98:99], 1, s[6:7]
	v_lshl_add_u64 v[98:99], v[98:99], 0, v[138:139]
	s_waitcnt lgkmcnt(0)
	v_pk_mul_f32 v[94:95], v[94:95], v[96:97] op_sel_hi:[1,0]
	v_pk_mul_f32 v[92:93], v[92:93], v[96:97] op_sel_hi:[1,0]
	v_pk_mul_f32 v[100:101], v[90:91], v[96:97] op_sel_hi:[1,0]
	v_pk_mul_f32 v[90:91], v[88:89], v[96:97] op_sel_hi:[1,0]
	v_cvt_pk_bf16_f32 v88, v92, v93
	v_cvt_pk_bf16_f32 v89, v94, v95
	v_pk_mul_f32 v[84:85], v[84:85], v[96:97] op_sel_hi:[1,0]
	v_cvt_pk_bf16_f32 v90, v90, v91
	v_cvt_pk_bf16_f32 v91, v100, v101
	global_store_dwordx4 v[98:99], v[88:91], off
	v_pk_mul_f32 v[86:87], v[86:87], v[96:97] op_sel_hi:[1,0]
	s_nop 0
	v_pk_mul_f32 v[88:89], v[82:83], v[96:97] op_sel_hi:[1,0]
	v_pk_mul_f32 v[82:83], v[80:81], v[96:97] op_sel_hi:[1,0]
	v_cvt_pk_bf16_f32 v80, v84, v85
	v_cvt_pk_bf16_f32 v81, v86, v87
	s_nop 0
	v_cvt_pk_bf16_f32 v82, v82, v83
	v_cvt_pk_bf16_f32 v83, v88, v89
	global_store_dwordx4 v[98:99], v[80:83], off offset:256
	ds_read_b32 v80, v145 offset:192
	s_nop 0
	v_or_b32_e32 v81, 48, v144
	v_mad_i64_i32 v[82:83], s[22:23], v81, s0, 0
	v_lshl_add_u64 v[82:83], v[82:83], 1, s[6:7]
	v_lshl_add_u64 v[82:83], v[82:83], 0, v[138:139]
	s_waitcnt lgkmcnt(0)
	v_pk_mul_f32 v[78:79], v[78:79], v[80:81] op_sel_hi:[1,0]
	v_pk_mul_f32 v[76:77], v[76:77], v[80:81] op_sel_hi:[1,0]
	v_pk_mul_f32 v[84:85], v[74:75], v[80:81] op_sel_hi:[1,0]
	v_pk_mul_f32 v[74:75], v[72:73], v[80:81] op_sel_hi:[1,0]
	v_cvt_pk_bf16_f32 v72, v76, v77
	v_cvt_pk_bf16_f32 v73, v78, v79
	v_pk_mul_f32 v[68:69], v[68:69], v[80:81] op_sel_hi:[1,0]
	v_cvt_pk_bf16_f32 v74, v74, v75
	v_cvt_pk_bf16_f32 v75, v84, v85
	global_store_dwordx4 v[82:83], v[72:75], off
	v_pk_mul_f32 v[70:71], v[70:71], v[80:81] op_sel_hi:[1,0]
	s_nop 0
	v_pk_mul_f32 v[72:73], v[66:67], v[80:81] op_sel_hi:[1,0]
	v_pk_mul_f32 v[66:67], v[64:65], v[80:81] op_sel_hi:[1,0]
	v_cvt_pk_bf16_f32 v64, v68, v69
	v_cvt_pk_bf16_f32 v65, v70, v71
	s_nop 0
	v_cvt_pk_bf16_f32 v66, v66, v67
	v_cvt_pk_bf16_f32 v67, v72, v73
	global_store_dwordx4 v[82:83], v[64:67], off offset:256
	ds_read_b32 v64, v145 offset:512
	s_nop 0
	v_add_u32_e32 v65, 0x80, v144
	v_mad_i64_i32 v[66:67], s[22:23], v65, s0, 0
	v_lshl_add_u64 v[66:67], v[66:67], 1, s[6:7]
	v_lshl_add_u64 v[66:67], v[66:67], 0, v[138:139]
	s_waitcnt lgkmcnt(0)
; __device__ __forceinline__ unsigned cvt_pk_bf16(float lo, float hi) { unsigned r; asm volatile("v_cvt_pk_bf16_f32 %0, %1, %2" : "=v"(r) : "v"(lo), "v"(hi)); return r; }
; #define PG8_BAR __builtin_amdgcn_s_barrier()
;     __device__ __forceinline__ void operator()(f32x4 (&acc)[2][2][4][2], const Unit& u, int wr, int wc, int fr, int fq, const LAS float* rtab) const {
;     ...
;             for (int m = 0; m < 4; ++m) { bf16_t* rowp = O + (size_t)(row0 + ai * HALF + m * 16) * ldc + col0; const float r = rtab[ai * HALF + wr * 64 + m * 16 + fr];
; #pragma unroll
;                 for (int bj = 0; bj < 2; ++bj) { const f32x4 v0 = acc[ai][bj][m][0] * r, v1 = acc[ai][bj][m][1] * r;
;                     u32x4 w; w.x = cvt_pk_bf16(v0[0], v0[1]); w.y = cvt_pk_bf16(v0[2], v0[3]); w.z = cvt_pk_bf16(v1[0], v1[1]); w.w = cvt_pk_bf16(v1[2], v1[3]);
;                     *(u32x4*)(rowp + bj * HALF) = w; } }
; template <class Epi, bool KREV = false>
; __device__ __forceinline__ void gemm_phase(LAS unsigned char* lds, const Gemm g, const StaticOrder& S, const Epi& E, int wave_s) {
;     ...
;         if (!has_next) break;
; #pragma unroll
;         for (int a = 0; a < 2; ++a)
; #pragma unroll
;             for (int b = 0; b < 2; ++b)
; #pragma unroll
;                 for (int m = 0; m < 4; ++m)
; #pragma unroll
;                     for (int n = 0; n < 2; ++n) acc[a][b][m][n] = (f32x4){0.f, 0.f, 0.f, 0.f};
;         cur = nxt; cA = nA; cB = nB; ++ui;
;         if (wr == 1) PG8_BAR;
	v_pk_mul_f32 v[62:63], v[62:63], v[64:65] op_sel_hi:[1,0]
	v_pk_mul_f32 v[60:61], v[60:61], v[64:65] op_sel_hi:[1,0]
	v_pk_mul_f32 v[68:69], v[58:59], v[64:65] op_sel_hi:[1,0]
	v_pk_mul_f32 v[58:59], v[56:57], v[64:65] op_sel_hi:[1,0]
	v_cvt_pk_bf16_f32 v56, v60, v61
	v_cvt_pk_bf16_f32 v57, v62, v63
	v_pk_mul_f32 v[52:53], v[52:53], v[64:65] op_sel_hi:[1,0]
	v_cvt_pk_bf16_f32 v58, v58, v59
	v_cvt_pk_bf16_f32 v59, v68, v69
	global_store_dwordx4 v[66:67], v[56:59], off
	v_pk_mul_f32 v[54:55], v[54:55], v[64:65] op_sel_hi:[1,0]
	s_nop 0
	v_pk_mul_f32 v[56:57], v[50:51], v[64:65] op_sel_hi:[1,0]
	v_pk_mul_f32 v[50:51], v[48:49], v[64:65] op_sel_hi:[1,0]
	v_cvt_pk_bf16_f32 v48, v52, v53
	v_cvt_pk_bf16_f32 v49, v54, v55
	s_nop 0
	v_cvt_pk_bf16_f32 v50, v50, v51
	v_cvt_pk_bf16_f32 v51, v56, v57
	global_store_dwordx4 v[66:67], v[48:51], off offset:256
	ds_read_b32 v48, v145 offset:576
	s_nop 0
	v_add_u32_e32 v49, 0x90, v144
	v_mad_i64_i32 v[50:51], s[22:23], v49, s0, 0
	v_lshl_add_u64 v[50:51], v[50:51], 1, s[6:7]
	v_lshl_add_u64 v[50:51], v[50:51], 0, v[138:139]
	s_waitcnt lgkmcnt(0)
	v_pk_mul_f32 v[46:47], v[46:47], v[48:49] op_sel_hi:[1,0]
	v_pk_mul_f32 v[44:45], v[44:45], v[48:49] op_sel_hi:[1,0]
	v_pk_mul_f32 v[52:53], v[42:43], v[48:49] op_sel_hi:[1,0]
	v_pk_mul_f32 v[42:43], v[40:41], v[48:49] op_sel_hi:[1,0]
	v_cvt_pk_bf16_f32 v40, v44, v45
	v_cvt_pk_bf16_f32 v41, v46, v47
	v_pk_mul_f32 v[36:37], v[36:37], v[48:49] op_sel_hi:[1,0]
	v_cvt_pk_bf16_f32 v42, v42, v43
	v_cvt_pk_bf16_f32 v43, v52, v53
	global_store_dwordx4 v[50:51], v[40:43], off
	v_pk_mul_f32 v[38:39], v[38:39], v[48:49] op_sel_hi:[1,0]
	s_nop 0
	v_pk_mul_f32 v[40:41], v[34:35], v[48:49] op_sel_hi:[1,0]
	v_pk_mul_f32 v[34:35], v[32:33], v[48:49] op_sel_hi:[1,0]
	v_cvt_pk_bf16_f32 v32, v36, v37
	v_cvt_pk_bf16_f32 v33, v38, v39
	s_nop 0
	v_cvt_pk_bf16_f32 v34, v34, v35
	v_cvt_pk_bf16_f32 v35, v40, v41
	global_store_dwordx4 v[50:51], v[32:35], off offset:256
	ds_read_b32 v32, v145 offset:640
	s_nop 0
	v_add_u32_e32 v33, 0xa0, v144
	v_mad_i64_i32 v[34:35], s[22:23], v33, s0, 0
	v_lshl_add_u64 v[34:35], v[34:35], 1, s[6:7]
	v_lshl_add_u64 v[34:35], v[34:35], 0, v[138:139]
	s_waitcnt lgkmcnt(0)
	v_pk_mul_f32 v[30:31], v[30:31], v[32:33] op_sel_hi:[1,0]
	v_pk_mul_f32 v[28:29], v[28:29], v[32:33] op_sel_hi:[1,0]
	v_pk_mul_f32 v[36:37], v[26:27], v[32:33] op_sel_hi:[1,0]
	v_pk_mul_f32 v[26:27], v[24:25], v[32:33] op_sel_hi:[1,0]
	v_cvt_pk_bf16_f32 v24, v28, v29
	v_cvt_pk_bf16_f32 v25, v30, v31
	v_pk_mul_f32 v[20:21], v[20:21], v[32:33] op_sel_hi:[1,0]
	v_cvt_pk_bf16_f32 v26, v26, v27
	v_cvt_pk_bf16_f32 v27, v36, v37
	global_store_dwordx4 v[34:35], v[24:27], off
	v_pk_mul_f32 v[22:23], v[22:23], v[32:33] op_sel_hi:[1,0]
	s_nop 0
	v_pk_mul_f32 v[24:25], v[18:19], v[32:33] op_sel_hi:[1,0]
	v_pk_mul_f32 v[18:19], v[16:17], v[32:33] op_sel_hi:[1,0]
	v_cvt_pk_bf16_f32 v16, v20, v21
	v_cvt_pk_bf16_f32 v17, v22, v23
	s_nop 0
	v_cvt_pk_bf16_f32 v18, v18, v19
	v_cvt_pk_bf16_f32 v19, v24, v25
	global_store_dwordx4 v[34:35], v[16:19], off offset:256
	ds_read_b32 v16, v145 offset:704
	s_nop 0
	v_add_u32_e32 v17, 0xb0, v144
	v_mad_i64_i32 v[18:19], s[22:23], v17, s0, 0
	v_lshl_add_u64 v[18:19], v[18:19], 1, s[6:7]
	v_lshl_add_u64 v[18:19], v[18:19], 0, v[138:139]
	s_waitcnt lgkmcnt(0)
	v_pk_mul_f32 v[14:15], v[14:15], v[16:17] op_sel_hi:[1,0]
	v_pk_mul_f32 v[12:13], v[12:13], v[16:17] op_sel_hi:[1,0]
	v_pk_mul_f32 v[20:21], v[10:11], v[16:17] op_sel_hi:[1,0]
	v_pk_mul_f32 v[10:11], v[8:9], v[16:17] op_sel_hi:[1,0]
	v_cvt_pk_bf16_f32 v8, v12, v13
	v_cvt_pk_bf16_f32 v9, v14, v15
	v_pk_mul_f32 v[6:7], v[6:7], v[16:17] op_sel_hi:[1,0]
	v_cvt_pk_bf16_f32 v10, v10, v11
	v_cvt_pk_bf16_f32 v11, v20, v21
	global_store_dwordx4 v[18:19], v[8:11], off
	v_pk_mul_f32 v[4:5], v[4:5], v[16:17] op_sel_hi:[1,0]
	s_nop 0
	v_pk_mul_f32 v[8:9], v[2:3], v[16:17] op_sel_hi:[1,0]
	v_pk_mul_f32 v[2:3], v[0:1], v[16:17] op_sel_hi:[1,0]
	v_cvt_pk_bf16_f32 v0, v4, v5
	v_cvt_pk_bf16_f32 v1, v6, v7
	s_nop 0
	v_cvt_pk_bf16_f32 v2, v2, v3
	v_cvt_pk_bf16_f32 v3, v8, v9
	global_store_dwordx4 v[18:19], v[0:3], off offset:256
	s_cbranch_vccnz .LBB0_160
	s_andn2_b64 vcc, exec, s[16:17]
	s_cbranch_vccnz .LBB0_159
	s_branch .LBB0_159

; #define PG8_BAR __builtin_amdgcn_s_barrier()
; template <class Epi, bool KREV = false>
; __device__ __forceinline__ void gemm_phase(LAS unsigned char* lds, const Gemm g, const StaticOrder& S, const Epi& E, int wave_s) {
;     ...
;         const bool has_next = S.next(ui + 1, nxt);
;         const char* nA = has_next ? (const char*)g.A + (size_t)nxt.pm * tstep + k0off : cA; const char* nB = has_next ? (const char*)g.Bt + (size_t)nxt.pn * bunit + k0off : cB;
;     ...
; #pragma unroll
;         for (int a = 0; a < 2; ++a)
; #pragma unroll
;             for (int b = 0; b < 2; ++b)
; #pragma unroll
;                 for (int m = 0; m < 4; ++m)
; #pragma unroll
;                     for (int n = 0; n < 2; ++n) acc[a][b][m][n] = (f32x4){0.f, 0.f, 0.f, 0.f};
;         cur = nxt; cA = nA; cB = nB; ++ui;
;         if (wr == 1) PG8_BAR;
.LBB0_639:
	s_add_i32 s43, s43, 1
	s_mov_b32 s44, s8
	s_lshl_b32 s8, s43, 5
	s_add_i32 s8, s8, s0
	s_cmp_lt_i32 s8, 64
	s_cselect_b64 s[20:21], -1, 0
	s_ashr_i32 s8, s8, 3
	s_ashr_i32 s9, s8, 31
	s_mov_b64 s[22:23], s[16:17]
	s_lshl_b64 s[16:17], s[8:9], 20
	s_add_u32 s9, s4, s16
	s_addc_u32 s17, s5, s17
	s_add_u32 s16, s9, 0xf80
	s_addc_u32 s17, s17, 0
	s_and_b64 s[24:25], s[20:21], exec
	v_mov_b32_e32 v0, 0
	s_cselect_b32 s25, s17, s23
	s_cselect_b32 s24, s16, s22
	s_mov_b32 s9, 0
	v_mov_b32_e32 v1, v0
	v_mov_b32_e32 v2, v0
	v_mov_b32_e32 v3, v0
	v_mov_b32_e32 v4, v0
	v_mov_b32_e32 v5, v0
	v_mov_b32_e32 v6, v0
	v_mov_b32_e32 v7, v0
	v_mov_b32_e32 v16, v0
	v_mov_b32_e32 v17, v0
	v_mov_b32_e32 v18, v0
	v_mov_b32_e32 v19, v0
	v_mov_b32_e32 v20, v0
	v_mov_b32_e32 v21, v0
	v_mov_b32_e32 v22, v0
	v_mov_b32_e32 v23, v0
	v_mov_b32_e32 v32, v0
	v_mov_b32_e32 v33, v0
	v_mov_b32_e32 v34, v0
	v_mov_b32_e32 v35, v0
	v_mov_b32_e32 v36, v0
	v_mov_b32_e32 v37, v0
	v_mov_b32_e32 v38, v0
	v_mov_b32_e32 v39, v0
	v_mov_b32_e32 v48, v0
	v_mov_b32_e32 v49, v0
	v_mov_b32_e32 v50, v0
	v_mov_b32_e32 v51, v0
	v_mov_b32_e32 v52, v0
	v_mov_b32_e32 v53, v0
	v_mov_b32_e32 v54, v0
	v_mov_b32_e32 v55, v0
	v_mov_b32_e32 v8, v0
	v_mov_b32_e32 v9, v0
	v_mov_b32_e32 v10, v0
	v_mov_b32_e32 v11, v0
	v_mov_b32_e32 v12, v0
	v_mov_b32_e32 v13, v0
	v_mov_b32_e32 v14, v0
	v_mov_b32_e32 v15, v0
	v_mov_b32_e32 v24, v0
	v_mov_b32_e32 v25, v0
	v_mov_b32_e32 v26, v0
	v_mov_b32_e32 v27, v0
	v_mov_b32_e32 v28, v0
	v_mov_b32_e32 v29, v0
	v_mov_b32_e32 v30, v0
	v_mov_b32_e32 v31, v0
	v_mov_b32_e32 v40, v0
	v_mov_b32_e32 v41, v0
	v_mov_b32_e32 v42, v0
	v_mov_b32_e32 v43, v0
	v_mov_b32_e32 v44, v0
	v_mov_b32_e32 v45, v0
	v_mov_b32_e32 v46, v0
	v_mov_b32_e32 v47, v0
	v_mov_b32_e32 v56, v0
	v_mov_b32_e32 v57, v0
	v_mov_b32_e32 v58, v0
	v_mov_b32_e32 v59, v0
	v_mov_b32_e32 v60, v0
	v_mov_b32_e32 v61, v0
	v_mov_b32_e32 v62, v0
	v_mov_b32_e32 v63, v0
	v_mov_b32_e32 v64, v0
	v_mov_b32_e32 v65, v0
	v_mov_b32_e32 v66, v0
	v_mov_b32_e32 v67, v0
	v_mov_b32_e32 v68, v0
	v_mov_b32_e32 v69, v0
	v_mov_b32_e32 v70, v0
	v_mov_b32_e32 v71, v0
	v_mov_b32_e32 v80, v0
	v_mov_b32_e32 v81, v0
	v_mov_b32_e32 v82, v0
	v_mov_b32_e32 v83, v0
	v_mov_b32_e32 v84, v0
	v_mov_b32_e32 v85, v0
	v_mov_b32_e32 v86, v0
	v_mov_b32_e32 v87, v0
	v_mov_b32_e32 v96, v0
	v_mov_b32_e32 v97, v0
	v_mov_b32_e32 v98, v0
	v_mov_b32_e32 v99, v0
	v_mov_b32_e32 v100, v0
	v_mov_b32_e32 v101, v0
	v_mov_b32_e32 v102, v0
	v_mov_b32_e32 v103, v0
	v_mov_b32_e32 v116, v0
	v_mov_b32_e32 v117, v0
	v_mov_b32_e32 v118, v0
	v_mov_b32_e32 v119, v0
	v_mov_b32_e32 v128, v0
	v_mov_b32_e32 v129, v0
	v_mov_b32_e32 v130, v0
	v_mov_b32_e32 v131, v0
	v_mov_b32_e32 v72, v0
	v_mov_b32_e32 v73, v0
	v_mov_b32_e32 v74, v0
	v_mov_b32_e32 v75, v0
	v_mov_b32_e32 v76, v0
	v_mov_b32_e32 v77, v0
	v_mov_b32_e32 v78, v0
	v_mov_b32_e32 v79, v0
	v_mov_b32_e32 v88, v0
	v_mov_b32_e32 v89, v0
	v_mov_b32_e32 v90, v0
	v_mov_b32_e32 v91, v0
	v_mov_b32_e32 v92, v0
	v_mov_b32_e32 v93, v0
	v_mov_b32_e32 v94, v0
	v_mov_b32_e32 v95, v0
	v_mov_b32_e32 v104, v0
	v_mov_b32_e32 v105, v0
	v_mov_b32_e32 v106, v0
	v_mov_b32_e32 v107, v0
	v_mov_b32_e32 v108, v0
	v_mov_b32_e32 v109, v0
	v_mov_b32_e32 v110, v0
	v_mov_b32_e32 v111, v0
	v_mov_b32_e32 v120, v0
	v_mov_b32_e32 v121, v0
	v_mov_b32_e32 v122, v0
	v_mov_b32_e32 v123, v0
	v_mov_b32_e32 v132, v0
	v_mov_b32_e32 v133, v0
	v_mov_b32_e32 v134, v0
	v_mov_b32_e32 v135, v0
	s_cmp_eq_u32 s43, 1
	s_cbranch_scc1 .Lsb1
	s_andn2_b64 vcc, exec, s[10:11]
	s_cbranch_vccnz .Lsb1
	s_barrier
.Lsb1:
	s_branch .Lkr1_reads

; #define PG8_BAR __builtin_amdgcn_s_barrier()
;     __device__ __forceinline__ void operator()(f32x4 (&acc)[2][2][4][2], const Unit& u, int wr, int wc, int fr, int fq, const LAS float*) const {
;     ...
;             slot[(size_t)(u.pn * 4 + wc) * MT + row0 + k * HALF + fq * 16] = v; }
; template <class Epi, bool KREV = false>
; __device__ __forceinline__ void gemm_phase(LAS unsigned char* lds, const Gemm g, const StaticOrder& S, const Epi& E, int wave_s) {
;     ...
;         if (!has_next) break;
; #pragma unroll
;         for (int a = 0; a < 2; ++a)
; #pragma unroll
;             for (int b = 0; b < 2; ++b)
; #pragma unroll
;                 for (int m = 0; m < 4; ++m)
; #pragma unroll
;                     for (int n = 0; n < 2; ++n) acc[a][b][m][n] = (f32x4){0.f, 0.f, 0.f, 0.f};
;         cur = nxt; cA = nA; cB = nB; ++ui;
;         if (wr == 1) PG8_BAR;
.LBB0_667:
	s_or_b64 exec, exec, s[22:23]
	s_andn2_b64 vcc, exec, s[20:21]
	s_mov_b64 s[20:21], -1
	global_store_dword v[0:1], v4, off offset:512
	s_cbranch_vccnz .LBB0_638
	s_andn2_b64 vcc, exec, s[10:11]
	s_cbranch_vccnz .LBB0_637
	s_branch .LBB0_637

; #define PG8_STAGE(bufoff, gbase, voff) do { _Pragma("unroll") for (int _i = 0; _i < 2; ++_i) \
;         __builtin_amdgcn_global_load_lds((const unsigned*)((const char*)(gbase) + (voff)[_i]), (LAS unsigned*)(lds + (bufoff) + ldsw + _i * 8192), 16, 0, 0); } while (0)
; #define PG8_LDA(dst, b, h) do { _Pragma("unroll") for (int m = 0; m < 4; ++m) _Pragma("unroll") for (int k = 0; k < 2; ++k) dst[m][k] = *(const LAS bf16x8*)(lds + PG8_SA(b, h) + aoff + m * 2048 + k * 1024); } while (0)
; #define PG8_LDB(dst, b, h) do { _Pragma("unroll") for (int n = 0; n < 2; ++n) _Pragma("unroll") for (int k = 0; k < 2; ++k) dst[n][k] = *(const LAS bf16x8*)(lds + PG8_SB(b, h) + boff + n * 2048 + k * 1024); } while (0)
; #define PG8_BAR __builtin_amdgcn_s_barrier()
; #define PG8_SCHED __builtin_amdgcn_sched_barrier(0)
; template <class Epi, bool KREV = false>
; __device__ __forceinline__ void gemm_phase(LAS unsigned char* lds, const Gemm g, const StaticOrder& S, const Epi& E, int wave_s) {
;     ...
;         const bool has_next = S.next(ui + 1, nxt);
;         const char* nA = has_next ? (const char*)g.A + (size_t)nxt.pm * tstep + k0off : cA; const char* nB = has_next ? (const char*)g.Bt + (size_t)nxt.pn * bunit + k0off : cB;
;         for (int t = 0; t < nt; t += 2) {
;             const bool last = (t == nt - 2);
;             const char* a1 = cA + (size_t)(t + 1) * kstep;
;             const char* a2 = last ? nA : cA + (size_t)(t + 2) * kstep; const char* b2 = last ? nB : cB + (size_t)(t + 2) * kstep;
;             const char* a3 = a2 + kstep; const char* b3 = b2 + kstep;
;             PG8_LDB(B0, 0, 0); PG8_LDB(B1, 0, 1); PG8_SCHED; PG8_LDA(At, 0, 0); PG8_STAGE(PG8_SA(1, 1), a1 + hstep, voffA);
;     ...
; #pragma unroll
;         for (int a = 0; a < 2; ++a)
; #pragma unroll
;             for (int b = 0; b < 2; ++b)
; #pragma unroll
;                 for (int m = 0; m < 4; ++m)
; #pragma unroll
;                     for (int n = 0; n < 2; ++n) acc[a][b][m][n] = (f32x4){0.f, 0.f, 0.f, 0.f};
;         cur = nxt; cA = nA; cB = nB; ++ui;
;         if (wr == 1) PG8_BAR;
.LBB0_835:
	s_mov_b32 s1, s72
	s_add_i32 s72, s72, 1
	s_mov_b64 s[54:55], s[24:25]
	s_mov_b32 s0, s20
	s_mov_b32 s24, s20
	s_lshl_b32 s20, s72, 5
	s_add_i32 s20, s20, s61
	s_cmpk_lt_i32 s20, 0x160
	s_cselect_b64 s[52:53], -1, 0
	s_ashr_i32 s20, s20, 3
	s_mov_b64 s[56:57], s[22:23]
	s_and_b64 s[22:23], s[52:53], exec
	s_cselect_b32 s22, s20, s24
	s_cselect_b32 s24, s18, s18
	s_ashr_i32 s25, s24, 31
	s_lshl_b64 s[24:25], s[24:25], 20
	s_add_u32 s24, s62, s24
	s_addc_u32 s25, s63, s25
	s_and_b64 s[58:59], s[52:53], exec
	s_cselect_b32 s73, s25, s55
	s_cselect_b32 s74, s24, s54
	s_ashr_i32 s23, s22, 31
	s_lshl_b64 s[22:23], s[22:23], 19
	s_add_u32 s22, s64, s22
	s_addc_u32 s23, s65, s23
	s_and_b64 s[58:59], s[52:53], exec
	s_cselect_b32 s75, s23, s57
	s_cselect_b32 s77, s22, s56
	s_add_u32 s54, s54, 0x80080
	s_addc_u32 s55, s55, 0
	s_add_u32 s80, s56, 0x100
	v_mov_b32_e32 v40, 0
	s_addc_u32 s82, s57, 0
	s_mov_b32 s83, -2
	v_mov_b32_e32 v41, v40
	v_mov_b32_e32 v42, v40
	v_mov_b32_e32 v43, v40
	v_mov_b32_e32 v72, v40
	v_mov_b32_e32 v73, v40
	v_mov_b32_e32 v74, v40
	v_mov_b32_e32 v75, v40
	v_mov_b32_e32 v0, v40
	v_mov_b32_e32 v1, v40
	v_mov_b32_e32 v2, v40
	v_mov_b32_e32 v3, v40
	v_mov_b32_e32 v24, v40
	v_mov_b32_e32 v25, v40
	v_mov_b32_e32 v26, v40
	v_mov_b32_e32 v27, v40
	v_mov_b32_e32 v8, v40
	v_mov_b32_e32 v9, v40
	v_mov_b32_e32 v10, v40
	v_mov_b32_e32 v11, v40
	v_mov_b32_e32 v28, v40
	v_mov_b32_e32 v29, v40
	v_mov_b32_e32 v30, v40
	v_mov_b32_e32 v31, v40
	v_mov_b32_e32 v80, v40
	v_mov_b32_e32 v81, v40
	v_mov_b32_e32 v82, v40
	v_mov_b32_e32 v83, v40
	v_mov_b32_e32 v84, v40
	v_mov_b32_e32 v85, v40
	v_mov_b32_e32 v86, v40
	v_mov_b32_e32 v87, v40
	v_mov_b32_e32 v56, v40
	v_mov_b32_e32 v57, v40
	v_mov_b32_e32 v58, v40
	v_mov_b32_e32 v59, v40
	v_mov_b32_e32 v76, v40
	v_mov_b32_e32 v77, v40
	v_mov_b32_e32 v78, v40
	v_mov_b32_e32 v79, v40
	v_mov_b32_e32 v4, v40
	v_mov_b32_e32 v5, v40
	v_mov_b32_e32 v6, v40
	v_mov_b32_e32 v7, v40
	v_mov_b32_e32 v32, v40
	v_mov_b32_e32 v33, v40
	v_mov_b32_e32 v34, v40
	v_mov_b32_e32 v35, v40
	v_mov_b32_e32 v12, v40
	v_mov_b32_e32 v13, v40
	v_mov_b32_e32 v14, v40
	v_mov_b32_e32 v15, v40
	v_mov_b32_e32 v36, v40
	v_mov_b32_e32 v37, v40
	v_mov_b32_e32 v38, v40
	v_mov_b32_e32 v39, v40
	v_mov_b32_e32 v88, v40
	v_mov_b32_e32 v89, v40
	v_mov_b32_e32 v90, v40
	v_mov_b32_e32 v91, v40
	v_mov_b32_e32 v92, v40
	v_mov_b32_e32 v93, v40
	v_mov_b32_e32 v94, v40
	v_mov_b32_e32 v95, v40
	v_mov_b32_e32 v96, v40
	v_mov_b32_e32 v97, v40
	v_mov_b32_e32 v98, v40
	v_mov_b32_e32 v99, v40
	v_mov_b32_e32 v100, v40
	v_mov_b32_e32 v101, v40
	v_mov_b32_e32 v102, v40
	v_mov_b32_e32 v103, v40
	v_mov_b32_e32 v16, v40
	v_mov_b32_e32 v17, v40
	v_mov_b32_e32 v18, v40
	v_mov_b32_e32 v19, v40
	v_mov_b32_e32 v44, v40
	v_mov_b32_e32 v45, v40
	v_mov_b32_e32 v46, v40
	v_mov_b32_e32 v47, v40
	v_mov_b32_e32 v48, v40
	v_mov_b32_e32 v49, v40
	v_mov_b32_e32 v50, v40
	v_mov_b32_e32 v51, v40
	v_mov_b32_e32 v52, v40
	v_mov_b32_e32 v53, v40
	v_mov_b32_e32 v54, v40
	v_mov_b32_e32 v55, v40
	v_mov_b32_e32 v112, v40
	v_mov_b32_e32 v113, v40
	v_mov_b32_e32 v114, v40
	v_mov_b32_e32 v115, v40
	v_mov_b32_e32 v116, v40
	v_mov_b32_e32 v117, v40
	v_mov_b32_e32 v118, v40
	v_mov_b32_e32 v119, v40
	v_mov_b32_e32 v104, v40
	v_mov_b32_e32 v105, v40
	v_mov_b32_e32 v106, v40
	v_mov_b32_e32 v107, v40
	v_mov_b32_e32 v108, v40
	v_mov_b32_e32 v109, v40
	v_mov_b32_e32 v110, v40
	v_mov_b32_e32 v111, v40
	v_mov_b32_e32 v20, v40
	v_mov_b32_e32 v21, v40
	v_mov_b32_e32 v22, v40
	v_mov_b32_e32 v23, v40
	v_mov_b32_e32 v60, v40
	v_mov_b32_e32 v61, v40
	v_mov_b32_e32 v62, v40
	v_mov_b32_e32 v63, v40
	v_mov_b32_e32 v64, v40
	v_mov_b32_e32 v65, v40
	v_mov_b32_e32 v66, v40
	v_mov_b32_e32 v67, v40
	v_mov_b32_e32 v68, v40
	v_mov_b32_e32 v69, v40
	v_mov_b32_e32 v70, v40
	v_mov_b32_e32 v71, v40
	v_mov_b32_e32 v120, v40
	v_mov_b32_e32 v121, v40
	v_mov_b32_e32 v122, v40
	v_mov_b32_e32 v123, v40
	v_mov_b32_e32 v124, v40
	v_mov_b32_e32 v125, v40
	v_mov_b32_e32 v126, v40
	v_mov_b32_e32 v127, v40
	s_cmp_eq_u32 s1, 0
	s_cbranch_scc1 .Lsb2
	s_andn2_b64 vcc, exec, s[26:27]
	s_cbranch_vccnz .Lsb2
	s_barrier
.Lsb2:
.LBB0_836:
	v_add_u32_e32 v154, 0x10000, v135
	v_add_u32_e32 v170, 0x14000, v135
	ds_read_b128 v[142:145], v154
	ds_read_b128 v[146:149], v154 offset:1024
	ds_read_b128 v[150:153], v154 offset:2048
	ds_read_b128 v[154:157], v154 offset:3072
	ds_read_b128 v[158:161], v170
	ds_read_b128 v[162:165], v170 offset:1024
	ds_read_b128 v[166:169], v170 offset:2048
	ds_read_b128 v[170:173], v170 offset:3072
	ds_read_b128 v[178:181], v194
	ds_read_b128 v[182:185], v194 offset:1024
	ds_read_b128 v[186:189], v194 offset:2048
	ds_read_b128 v[196:199], v194 offset:3072
	ds_read_b128 v[200:203], v194 offset:4096
	ds_read_b128 v[204:207], v194 offset:5120
	ds_read_b128 v[218:221], v194 offset:6144
	ds_read_b128 v[222:225], v194 offset:7168
	s_add_u32 s56, s54, 0xfff80080
	s_addc_u32 s57, s55, -1
	s_add_i32 s84, 0, 0x10000
	s_cmp_eq_u32 s83, 28
	s_cselect_b32 s59, s73, s57
	s_cselect_b32 s58, s74, s56
	s_cselect_b32 s57, s75, s82
	s_cselect_b32 s56, s77, s80
	s_add_i32 s86, 0, 0x14000
	s_add_i32 m0, s19, 0xc000
	s_nop 0
	global_load_lds_dwordx4 v138, s[54:55]
	s_add_i32 m0, s19, 0xe000
	s_nop 0
	global_load_lds_dwordx4 v140, s[54:55]
	s_waitcnt vmcnt(8)
	s_waitcnt lgkmcnt(0)
	s_barrier
; #define PG8_STAGE(bufoff, gbase, voff) do { _Pragma("unroll") for (int _i = 0; _i < 2; ++_i) \
;         __builtin_amdgcn_global_load_lds((const unsigned*)((const char*)(gbase) + (voff)[_i]), (LAS unsigned*)(lds + (bufoff) + ldsw + _i * 8192), 16, 0, 0); } while (0)
; #define PG8_LDA(dst, b, h) do { _Pragma("unroll") for (int m = 0; m < 4; ++m) _Pragma("unroll") for (int k = 0; k < 2; ++k) dst[m][k] = *(const LAS bf16x8*)(lds + PG8_SA(b, h) + aoff + m * 2048 + k * 1024); } while (0)
; #define PG8_MMA(ai, bj, At, Bt) do { __builtin_amdgcn_s_setprio(1); _Pragma("unroll") for (int m = 0; m < 4; ++m) _Pragma("unroll") for (int n = 0; n < 2; ++n) _Pragma("unroll") for (int k = 0; k < 2; ++k) \
;         acc[ai][bj][m][n] = __builtin_amdgcn_mfma_f32_16x16x32_bf16(Bt[n][k], At[m][k], acc[ai][bj][m][n], 0, 0, 0); __builtin_amdgcn_s_setprio(0); } while (0)
; #define PG8_WAIT_V(n) asm volatile("s_waitcnt vmcnt(" #n ")" ::: "memory")
; #define PG8_WAIT_L(n) asm volatile("s_waitcnt lgkmcnt(" #n ")" ::: "memory")
; #define PG8_BAR __builtin_amdgcn_s_barrier()
; #define PG8_SCHED __builtin_amdgcn_sched_barrier(0)
; template <class Epi, bool KREV = false>
; __device__ __forceinline__ void gemm_phase(LAS unsigned char* lds, const Gemm g, const StaticOrder& S, const Epi& E, int wave_s) {
;     ...
;             PG8_WAIT_V(8); PG8_WAIT_L(0); PG8_BAR; PG8_MMA(0, 0, At, B0); PG8_MMA(0, 1, At, B1); PG8_BAR; PG8_SCHED;
;             PG8_LDA(At, 0, 1); PG8_STAGE(PG8_SB(0, 0), b2, voffB); PG8_STAGE(PG8_SB(0, 1), b2 + bh, voffB); PG8_STAGE(PG8_SA(0, 0), a2, voffA);
;             PG8_WAIT_V(8); PG8_WAIT_L(0); PG8_BAR; PG8_MMA(1, 0, At, B0); PG8_MMA(1, 1, At, B1); PG8_BAR; PG8_SCHED;
	s_setprio 1
	s_waitcnt lgkmcnt(0)
	v_mfma_f32_16x16x32_bf16 v[124:127], v[142:145], v[178:181], v[124:127]
	v_mfma_f32_16x16x32_bf16 v[120:123], v[150:153], v[178:181], v[120:123]
	v_mfma_f32_16x16x32_bf16 v[68:71], v[142:145], v[186:189], v[68:71]
	v_mfma_f32_16x16x32_bf16 v[64:67], v[150:153], v[186:189], v[64:67]
	v_mfma_f32_16x16x32_bf16 v[60:63], v[142:145], v[200:203], v[60:63]
	v_mfma_f32_16x16x32_bf16 v[20:23], v[150:153], v[200:203], v[20:23]
	v_mfma_f32_16x16x32_bf16 v[108:111], v[142:145], v[218:221], v[108:111]
	v_mfma_f32_16x16x32_bf16 v[104:107], v[150:153], v[218:221], v[104:107]
	v_mfma_f32_16x16x32_bf16 v[124:127], v[146:149], v[182:185], v[124:127]
	v_mfma_f32_16x16x32_bf16 v[120:123], v[154:157], v[182:185], v[120:123]
	v_mfma_f32_16x16x32_bf16 v[68:71], v[146:149], v[196:199], v[68:71]
	v_mfma_f32_16x16x32_bf16 v[64:67], v[154:157], v[196:199], v[64:67]
	v_mfma_f32_16x16x32_bf16 v[60:63], v[146:149], v[204:207], v[60:63]
	v_mfma_f32_16x16x32_bf16 v[20:23], v[154:157], v[204:207], v[20:23]
	v_mfma_f32_16x16x32_bf16 v[108:111], v[146:149], v[222:225], v[108:111]
	v_mfma_f32_16x16x32_bf16 v[104:107], v[154:157], v[222:225], v[104:107]
	s_setprio 0
	s_setprio 1
	v_mfma_f32_16x16x32_bf16 v[116:119], v[158:161], v[178:181], v[116:119]
	v_mfma_f32_16x16x32_bf16 v[112:115], v[166:169], v[178:181], v[112:115]
	v_mfma_f32_16x16x32_bf16 v[52:55], v[158:161], v[186:189], v[52:55]
	v_mfma_f32_16x16x32_bf16 v[48:51], v[166:169], v[186:189], v[48:51]
	v_mfma_f32_16x16x32_bf16 v[44:47], v[158:161], v[200:203], v[44:47]
	v_mfma_f32_16x16x32_bf16 v[16:19], v[166:169], v[200:203], v[16:19]
	v_mfma_f32_16x16x32_bf16 v[100:103], v[158:161], v[218:221], v[100:103]
	v_mfma_f32_16x16x32_bf16 v[96:99], v[166:169], v[218:221], v[96:99]
	v_mfma_f32_16x16x32_bf16 v[116:119], v[162:165], v[182:185], v[116:119]
	v_mfma_f32_16x16x32_bf16 v[112:115], v[170:173], v[182:185], v[112:115]
	v_mfma_f32_16x16x32_bf16 v[52:55], v[162:165], v[196:199], v[52:55]
	v_mfma_f32_16x16x32_bf16 v[48:51], v[170:173], v[196:199], v[48:51]
	v_mfma_f32_16x16x32_bf16 v[44:47], v[162:165], v[204:207], v[44:47]
	v_mfma_f32_16x16x32_bf16 v[16:19], v[170:173], v[204:207], v[16:19]
	v_mfma_f32_16x16x32_bf16 v[100:103], v[162:165], v[222:225], v[100:103]
	s_barrier
	v_mfma_f32_16x16x32_bf16 v[96:99], v[170:173], v[222:225], v[96:99]
	s_setprio 0
	s_add_u32 s98, s56, s2
	s_addc_u32 s99, s57, s3
	s_add_u32 s100, s58, s2
	s_addc_u32 s101, s59, s3
	s_add_i32 s84, s84, s66
	s_mov_b32 m0, s84
	ds_read_b128 v[178:181], v194 offset:16384
	ds_read_b128 v[182:185], v194 offset:17408
	ds_read_b128 v[186:189], v194 offset:18432
	ds_read_b128 v[196:199], v194 offset:19456
	ds_read_b128 v[200:203], v194 offset:20480
	ds_read_b128 v[204:207], v194 offset:21504
	ds_read_b128 v[218:221], v194 offset:22528
	ds_read_b128 v[222:225], v194 offset:23552
	global_load_lds_dwordx4 v176, s[56:57]
	s_add_i32 m0, s84, 0x2000
	s_add_u32 s84, s56, 0x1600000
	s_addc_u32 s85, s57, 0
	s_add_i32 s86, s86, s66
	global_load_lds_dwordx4 v132, s[56:57]
	s_mov_b32 m0, s86
	s_nop 0
	global_load_lds_dwordx4 v176, s[84:85]
	s_add_i32 m0, s86, 0x2000
	s_nop 0
	global_load_lds_dwordx4 v132, s[84:85]
	s_mov_b32 m0, s19
	s_nop 0
	global_load_lds_dwordx4 v128, s[58:59]
	s_mov_b32 m0, s21
	s_nop 0
	global_load_lds_dwordx4 v130, s[58:59]
	s_waitcnt vmcnt(8)
	s_waitcnt lgkmcnt(0)
	s_barrier
	s_setprio 1
	s_waitcnt lgkmcnt(0)
	v_mfma_f32_16x16x32_bf16 v[92:95], v[142:145], v[178:181], v[92:95]
	v_mfma_f32_16x16x32_bf16 v[88:91], v[150:153], v[178:181], v[88:91]
	v_mfma_f32_16x16x32_bf16 v[36:39], v[142:145], v[186:189], v[36:39]
	v_mfma_f32_16x16x32_bf16 v[12:15], v[150:153], v[186:189], v[12:15]
	v_mfma_f32_16x16x32_bf16 v[32:35], v[142:145], v[200:203], v[32:35]
	v_mfma_f32_16x16x32_bf16 v[4:7], v[150:153], v[200:203], v[4:7]
	v_mfma_f32_16x16x32_bf16 v[76:79], v[142:145], v[218:221], v[76:79]
	v_mfma_f32_16x16x32_bf16 v[56:59], v[150:153], v[218:221], v[56:59]
	v_mfma_f32_16x16x32_bf16 v[92:95], v[146:149], v[182:185], v[92:95]
	v_mfma_f32_16x16x32_bf16 v[88:91], v[154:157], v[182:185], v[88:91]
	v_mfma_f32_16x16x32_bf16 v[36:39], v[146:149], v[196:199], v[36:39]
	v_mfma_f32_16x16x32_bf16 v[12:15], v[154:157], v[196:199], v[12:15]
	v_mfma_f32_16x16x32_bf16 v[32:35], v[146:149], v[204:207], v[32:35]
	v_mfma_f32_16x16x32_bf16 v[4:7], v[154:157], v[204:207], v[4:7]
	v_mfma_f32_16x16x32_bf16 v[76:79], v[146:149], v[222:225], v[76:79]
	v_mfma_f32_16x16x32_bf16 v[56:59], v[154:157], v[222:225], v[56:59]
	s_setprio 0
	s_setprio 1
	v_mfma_f32_16x16x32_bf16 v[84:87], v[158:161], v[178:181], v[84:87]
	v_mfma_f32_16x16x32_bf16 v[80:83], v[166:169], v[178:181], v[80:83]
	v_mfma_f32_16x16x32_bf16 v[28:31], v[158:161], v[186:189], v[28:31]
	v_mfma_f32_16x16x32_bf16 v[8:11], v[166:169], v[186:189], v[8:11]
	v_mfma_f32_16x16x32_bf16 v[24:27], v[158:161], v[200:203], v[24:27]
	v_mfma_f32_16x16x32_bf16 v[0:3], v[166:169], v[200:203], v[0:3]
	v_mfma_f32_16x16x32_bf16 v[72:75], v[158:161], v[218:221], v[72:75]
	v_mfma_f32_16x16x32_bf16 v[40:43], v[166:169], v[218:221], v[40:43]
	v_mfma_f32_16x16x32_bf16 v[84:87], v[162:165], v[182:185], v[84:87]
	v_mfma_f32_16x16x32_bf16 v[80:83], v[170:173], v[182:185], v[80:83]
	v_mfma_f32_16x16x32_bf16 v[28:31], v[162:165], v[196:199], v[28:31]
	v_mfma_f32_16x16x32_bf16 v[8:11], v[170:173], v[196:199], v[8:11]
	v_mfma_f32_16x16x32_bf16 v[24:27], v[162:165], v[204:207], v[24:27]
	v_mfma_f32_16x16x32_bf16 v[0:3], v[170:173], v[204:207], v[0:3]
	v_mfma_f32_16x16x32_bf16 v[72:75], v[162:165], v[222:225], v[72:75]
	s_barrier
; #define PG8_STAGE(bufoff, gbase, voff) do { _Pragma("unroll") for (int _i = 0; _i < 2; ++_i) \
;         __builtin_amdgcn_global_load_lds((const unsigned*)((const char*)(gbase) + (voff)[_i]), (LAS unsigned*)(lds + (bufoff) + ldsw + _i * 8192), 16, 0, 0); } while (0)
; #define PG8_LDA(dst, b, h) do { _Pragma("unroll") for (int m = 0; m < 4; ++m) _Pragma("unroll") for (int k = 0; k < 2; ++k) dst[m][k] = *(const LAS bf16x8*)(lds + PG8_SA(b, h) + aoff + m * 2048 + k * 1024); } while (0)
; #define PG8_LDB(dst, b, h) do { _Pragma("unroll") for (int n = 0; n < 2; ++n) _Pragma("unroll") for (int k = 0; k < 2; ++k) dst[n][k] = *(const LAS bf16x8*)(lds + PG8_SB(b, h) + boff + n * 2048 + k * 1024); } while (0)
; #define PG8_MMA(ai, bj, At, Bt) do { __builtin_amdgcn_s_setprio(1); _Pragma("unroll") for (int m = 0; m < 4; ++m) _Pragma("unroll") for (int n = 0; n < 2; ++n) _Pragma("unroll") for (int k = 0; k < 2; ++k) \
;         acc[ai][bj][m][n] = __builtin_amdgcn_mfma_f32_16x16x32_bf16(Bt[n][k], At[m][k], acc[ai][bj][m][n], 0, 0, 0); __builtin_amdgcn_s_setprio(0); } while (0)
; #define PG8_WAIT_V(n) asm volatile("s_waitcnt vmcnt(" #n ")" ::: "memory")
; #define PG8_WAIT_L(n) asm volatile("s_waitcnt lgkmcnt(" #n ")" ::: "memory")
; #define PG8_BAR __builtin_amdgcn_s_barrier()
; #define PG8_SCHED __builtin_amdgcn_sched_barrier(0)
; template <class Epi, bool KREV = false>
; __device__ __forceinline__ void gemm_phase(LAS unsigned char* lds, const Gemm g, const StaticOrder& S, const Epi& E, int wave_s) {
;     ...
;             PG8_LDB(B0, 1, 0); PG8_LDB(B1, 1, 1); PG8_SCHED; PG8_LDA(At, 1, 0); PG8_STAGE(PG8_SA(0, 1), a2 + hstep, voffA);
;             PG8_WAIT_V(8); PG8_WAIT_L(0); PG8_BAR; PG8_MMA(0, 0, At, B0); PG8_MMA(0, 1, At, B1); PG8_BAR; PG8_SCHED;
;             PG8_LDA(At, 1, 1); PG8_STAGE(PG8_SB(1, 0), b3, voffB); PG8_STAGE(PG8_SB(1, 1), b3 + bh, voffB); PG8_STAGE(PG8_SA(1, 0), a3, voffA);
;             PG8_WAIT_V(8); PG8_WAIT_L(0); PG8_BAR; PG8_MMA(1, 0, At, B0); PG8_MMA(1, 1, At, B1); PG8_BAR; PG8_SCHED;
;         }
;         if (wr == 0) PG8_BAR;
	v_mfma_f32_16x16x32_bf16 v[40:43], v[170:173], v[222:225], v[40:43]
	s_setprio 0
	s_add_i32 s84, 0, 0x18000
	s_add_i32 s85, 0, 0x1c000
	v_add_u32_e32 v154, s84, v135
	v_add_u32_e32 v170, s85, v135
	ds_read_b128 v[142:145], v154
	ds_read_b128 v[146:149], v154 offset:1024
	ds_read_b128 v[150:153], v154 offset:2048
	ds_read_b128 v[154:157], v154 offset:3072
	ds_read_b128 v[158:161], v170
	ds_read_b128 v[162:165], v170 offset:1024
	ds_read_b128 v[166:169], v170 offset:2048
	ds_read_b128 v[170:173], v170 offset:3072
	s_add_u32 s58, s58, 0x80000
	s_addc_u32 s59, s59, 0
	s_mov_b32 m0, s67
	ds_read_b128 v[178:181], v194 offset:32768
	ds_read_b128 v[182:185], v194 offset:33792
	ds_read_b128 v[186:189], v194 offset:34816
	ds_read_b128 v[196:199], v194 offset:35840
	ds_read_b128 v[200:203], v194 offset:36864
	ds_read_b128 v[204:207], v194 offset:37888
	ds_read_b128 v[218:221], v194 offset:38912
	ds_read_b128 v[222:225], v194 offset:39936
	global_load_lds_dwordx4 v128, s[58:59]
	s_mov_b32 m0, s68
	s_nop 0
	global_load_lds_dwordx4 v130, s[58:59]
	s_waitcnt vmcnt(8)
	s_waitcnt lgkmcnt(0)
	s_barrier
	s_setprio 1
	s_waitcnt lgkmcnt(0)
	v_mfma_f32_16x16x32_bf16 v[124:127], v[142:145], v[178:181], v[124:127]
	v_mfma_f32_16x16x32_bf16 v[120:123], v[150:153], v[178:181], v[120:123]
	v_mfma_f32_16x16x32_bf16 v[68:71], v[142:145], v[186:189], v[68:71]
	v_mfma_f32_16x16x32_bf16 v[64:67], v[150:153], v[186:189], v[64:67]
	v_mfma_f32_16x16x32_bf16 v[60:63], v[142:145], v[200:203], v[60:63]
	v_mfma_f32_16x16x32_bf16 v[20:23], v[150:153], v[200:203], v[20:23]
	v_mfma_f32_16x16x32_bf16 v[108:111], v[142:145], v[218:221], v[108:111]
	v_mfma_f32_16x16x32_bf16 v[104:107], v[150:153], v[218:221], v[104:107]
	v_mfma_f32_16x16x32_bf16 v[124:127], v[146:149], v[182:185], v[124:127]
	v_mfma_f32_16x16x32_bf16 v[120:123], v[154:157], v[182:185], v[120:123]
	v_mfma_f32_16x16x32_bf16 v[68:71], v[146:149], v[196:199], v[68:71]
	v_mfma_f32_16x16x32_bf16 v[64:67], v[154:157], v[196:199], v[64:67]
	v_mfma_f32_16x16x32_bf16 v[60:63], v[146:149], v[204:207], v[60:63]
	v_mfma_f32_16x16x32_bf16 v[20:23], v[154:157], v[204:207], v[20:23]
	v_mfma_f32_16x16x32_bf16 v[108:111], v[146:149], v[222:225], v[108:111]
	v_mfma_f32_16x16x32_bf16 v[104:107], v[154:157], v[222:225], v[104:107]
	s_setprio 0
	s_setprio 1
	v_mfma_f32_16x16x32_bf16 v[116:119], v[158:161], v[178:181], v[116:119]
	v_mfma_f32_16x16x32_bf16 v[112:115], v[166:169], v[178:181], v[112:115]
	v_mfma_f32_16x16x32_bf16 v[52:55], v[158:161], v[186:189], v[52:55]
	v_mfma_f32_16x16x32_bf16 v[48:51], v[166:169], v[186:189], v[48:51]
	v_mfma_f32_16x16x32_bf16 v[44:47], v[158:161], v[200:203], v[44:47]
	v_mfma_f32_16x16x32_bf16 v[16:19], v[166:169], v[200:203], v[16:19]
	v_mfma_f32_16x16x32_bf16 v[100:103], v[158:161], v[218:221], v[100:103]
	v_mfma_f32_16x16x32_bf16 v[96:99], v[166:169], v[218:221], v[96:99]
	v_mfma_f32_16x16x32_bf16 v[116:119], v[162:165], v[182:185], v[116:119]
	v_mfma_f32_16x16x32_bf16 v[112:115], v[170:173], v[182:185], v[112:115]
	v_mfma_f32_16x16x32_bf16 v[52:55], v[162:165], v[196:199], v[52:55]
	v_mfma_f32_16x16x32_bf16 v[48:51], v[170:173], v[196:199], v[48:51]
	v_mfma_f32_16x16x32_bf16 v[44:47], v[162:165], v[204:207], v[44:47]
	v_mfma_f32_16x16x32_bf16 v[16:19], v[170:173], v[204:207], v[16:19]
	v_mfma_f32_16x16x32_bf16 v[100:103], v[162:165], v[222:225], v[100:103]
	s_barrier
	v_mfma_f32_16x16x32_bf16 v[96:99], v[170:173], v[222:225], v[96:99]
	s_setprio 0
	s_add_i32 s58, s84, s66
	s_mov_b32 m0, s58
	ds_read_b128 v[178:181], v194 offset:49152
	ds_read_b128 v[182:185], v194 offset:50176
	ds_read_b128 v[186:189], v194 offset:51200
	ds_read_b128 v[196:199], v194 offset:52224
	ds_read_b128 v[200:203], v194 offset:53248
	ds_read_b128 v[204:207], v194 offset:54272
	ds_read_b128 v[218:221], v194 offset:55296
	ds_read_b128 v[222:225], v194 offset:56320
	global_load_lds_dwordx4 v176, s[98:99]
	s_add_i32 m0, s58, 0x2000
	s_add_u32 s56, s56, 0x1600080
	s_addc_u32 s57, s57, 0
	s_add_i32 s58, s85, s66
	global_load_lds_dwordx4 v132, s[98:99]
	s_mov_b32 m0, s58
	s_nop 0
	global_load_lds_dwordx4 v176, s[56:57]
	s_add_i32 m0, s58, 0x2000
	s_nop 0
	global_load_lds_dwordx4 v132, s[56:57]
	s_mov_b32 m0, s70
	s_nop 0
	global_load_lds_dwordx4 v128, s[100:101]
	s_mov_b32 m0, s71
	s_nop 0
	global_load_lds_dwordx4 v130, s[100:101]
	s_waitcnt vmcnt(8)
	s_waitcnt lgkmcnt(0)
	s_barrier
	s_setprio 1
	s_waitcnt lgkmcnt(0)
	v_mfma_f32_16x16x32_bf16 v[92:95], v[142:145], v[178:181], v[92:95]
	v_mfma_f32_16x16x32_bf16 v[88:91], v[150:153], v[178:181], v[88:91]
	v_mfma_f32_16x16x32_bf16 v[36:39], v[142:145], v[186:189], v[36:39]
	v_mfma_f32_16x16x32_bf16 v[12:15], v[150:153], v[186:189], v[12:15]
	v_mfma_f32_16x16x32_bf16 v[32:35], v[142:145], v[200:203], v[32:35]
	v_mfma_f32_16x16x32_bf16 v[4:7], v[150:153], v[200:203], v[4:7]
	v_mfma_f32_16x16x32_bf16 v[76:79], v[142:145], v[218:221], v[76:79]
	v_mfma_f32_16x16x32_bf16 v[56:59], v[150:153], v[218:221], v[56:59]
	v_mfma_f32_16x16x32_bf16 v[92:95], v[146:149], v[182:185], v[92:95]
	v_mfma_f32_16x16x32_bf16 v[88:91], v[154:157], v[182:185], v[88:91]
	v_mfma_f32_16x16x32_bf16 v[36:39], v[146:149], v[196:199], v[36:39]
	v_mfma_f32_16x16x32_bf16 v[12:15], v[154:157], v[196:199], v[12:15]
	v_mfma_f32_16x16x32_bf16 v[32:35], v[146:149], v[204:207], v[32:35]
	v_mfma_f32_16x16x32_bf16 v[4:7], v[154:157], v[204:207], v[4:7]
	v_mfma_f32_16x16x32_bf16 v[76:79], v[146:149], v[222:225], v[76:79]
	v_mfma_f32_16x16x32_bf16 v[56:59], v[154:157], v[222:225], v[56:59]
	s_setprio 0
	s_setprio 1
	v_mfma_f32_16x16x32_bf16 v[84:87], v[158:161], v[178:181], v[84:87]
	v_mfma_f32_16x16x32_bf16 v[80:83], v[166:169], v[178:181], v[80:83]
	v_mfma_f32_16x16x32_bf16 v[28:31], v[158:161], v[186:189], v[28:31]
	v_mfma_f32_16x16x32_bf16 v[8:11], v[166:169], v[186:189], v[8:11]
	v_mfma_f32_16x16x32_bf16 v[24:27], v[158:161], v[200:203], v[24:27]
	v_mfma_f32_16x16x32_bf16 v[0:3], v[166:169], v[200:203], v[0:3]
	v_mfma_f32_16x16x32_bf16 v[72:75], v[158:161], v[218:221], v[72:75]
	v_mfma_f32_16x16x32_bf16 v[40:43], v[166:169], v[218:221], v[40:43]
	v_mfma_f32_16x16x32_bf16 v[84:87], v[162:165], v[182:185], v[84:87]
	v_mfma_f32_16x16x32_bf16 v[80:83], v[170:173], v[182:185], v[80:83]
	v_mfma_f32_16x16x32_bf16 v[28:31], v[162:165], v[196:199], v[28:31]
	v_mfma_f32_16x16x32_bf16 v[8:11], v[170:173], v[196:199], v[8:11]
	s_add_i32 s83, s83, 2
	s_add_u32 s54, s54, 0x100
	s_addc_u32 s55, s55, 0
	v_mfma_f32_16x16x32_bf16 v[24:27], v[162:165], v[204:207], v[24:27]
	s_add_u32 s80, s80, 0x100
	s_addc_u32 s82, s82, 0
	v_mfma_f32_16x16x32_bf16 v[0:3], v[170:173], v[204:207], v[0:3]
	s_cmp_gt_u32 s83, 29
	v_mfma_f32_16x16x32_bf16 v[72:75], v[162:165], v[222:225], v[72:75]
	s_barrier
	v_mfma_f32_16x16x32_bf16 v[40:43], v[170:173], v[222:225], v[40:43]
	s_setprio 0
	s_cbranch_scc0 .LBB0_836
	s_and_b64 vcc, exec, s[38:39]
	s_cbranch_vccz .LBB0_839
	s_barrier

; #define PG8_BAR __builtin_amdgcn_s_barrier()
; template <class Epi, bool KREV = false>
; __device__ __forceinline__ void gemm_phase(LAS unsigned char* lds, const Gemm g, const StaticOrder& S, const Epi& E, int wave_s) {
;     ...
;         if (!has_next) break;
; #pragma unroll
;         for (int a = 0; a < 2; ++a)
; #pragma unroll
;             for (int b = 0; b < 2; ++b)
; #pragma unroll
;                 for (int m = 0; m < 4; ++m)
; #pragma unroll
;                     for (int n = 0; n < 2; ++n) acc[a][b][m][n] = (f32x4){0.f, 0.f, 0.f, 0.f};
;         cur = nxt; cA = nA; cB = nB; ++ui;
;         if (wr == 1) PG8_BAR;
.LBB0_856:
	s_andn2_b64 vcc, exec, s[26:27]
	s_cbranch_vccnz .LBB0_833
	s_branch .LBB0_833

; #define PG8_BAR __builtin_amdgcn_s_barrier()
; template <class Epi, bool KREV = false>
; __device__ __forceinline__ void gemm_phase(LAS unsigned char* lds, const Gemm g, const StaticOrder& S, const Epi& E, int wave_s) {
;     ...
;         const bool has_next = S.next(ui + 1, nxt);
;         const char* nA = has_next ? (const char*)g.A + (size_t)nxt.pm * tstep + k0off : cA; const char* nB = has_next ? (const char*)g.Bt + (size_t)nxt.pn * bunit + k0off : cB;
;     ...
; #pragma unroll
;         for (int a = 0; a < 2; ++a)
; #pragma unroll
;             for (int b = 0; b < 2; ++b)
; #pragma unroll
;                 for (int m = 0; m < 4; ++m)
; #pragma unroll
;                     for (int n = 0; n < 2; ++n) acc[a][b][m][n] = (f32x4){0.f, 0.f, 0.f, 0.f};
;         cur = nxt; cA = nA; cB = nB; ++ui;
;         if (wr == 1) PG8_BAR;
.LBB0_1022:
	s_and_b64 s[20:21], s[14:15], exec
	s_cselect_b32 s21, s11, s19
	s_cselect_b32 s20, s10, s18
	s_add_u32 s42, s18, 0x160000
	v_mov_b32_e32 v0, 0
	s_addc_u32 s43, s19, 0
	s_mov_b32 s44, 0
	v_mov_b32_e32 v1, v0
	v_mov_b32_e32 v2, v0
	v_mov_b32_e32 v3, v0
	v_mov_b32_e32 v4, v0
	v_mov_b32_e32 v5, v0
	v_mov_b32_e32 v6, v0
	v_mov_b32_e32 v7, v0
	v_mov_b32_e32 v16, v0
	v_mov_b32_e32 v17, v0
	v_mov_b32_e32 v18, v0
	v_mov_b32_e32 v19, v0
	v_mov_b32_e32 v20, v0
	v_mov_b32_e32 v21, v0
	v_mov_b32_e32 v22, v0
	v_mov_b32_e32 v23, v0
	v_mov_b32_e32 v32, v0
	v_mov_b32_e32 v33, v0
	v_mov_b32_e32 v34, v0
	v_mov_b32_e32 v35, v0
	v_mov_b32_e32 v36, v0
	v_mov_b32_e32 v37, v0
	v_mov_b32_e32 v38, v0
	v_mov_b32_e32 v39, v0
	v_mov_b32_e32 v48, v0
	v_mov_b32_e32 v49, v0
	v_mov_b32_e32 v50, v0
	v_mov_b32_e32 v51, v0
	v_mov_b32_e32 v52, v0
	v_mov_b32_e32 v53, v0
	v_mov_b32_e32 v54, v0
	v_mov_b32_e32 v55, v0
	v_mov_b32_e32 v8, v0
	v_mov_b32_e32 v9, v0
	v_mov_b32_e32 v10, v0
	v_mov_b32_e32 v11, v0
	v_mov_b32_e32 v12, v0
	v_mov_b32_e32 v13, v0
	v_mov_b32_e32 v14, v0
	v_mov_b32_e32 v15, v0
	v_mov_b32_e32 v24, v0
	v_mov_b32_e32 v25, v0
	v_mov_b32_e32 v26, v0
	v_mov_b32_e32 v27, v0
	v_mov_b32_e32 v28, v0
	v_mov_b32_e32 v29, v0
	v_mov_b32_e32 v30, v0
	v_mov_b32_e32 v31, v0
	v_mov_b32_e32 v40, v0
	v_mov_b32_e32 v41, v0
	v_mov_b32_e32 v42, v0
	v_mov_b32_e32 v43, v0
	v_mov_b32_e32 v44, v0
	v_mov_b32_e32 v45, v0
	v_mov_b32_e32 v46, v0
	v_mov_b32_e32 v47, v0
	v_mov_b32_e32 v56, v0
	v_mov_b32_e32 v57, v0
	v_mov_b32_e32 v58, v0
	v_mov_b32_e32 v59, v0
	v_mov_b32_e32 v60, v0
	v_mov_b32_e32 v61, v0
	v_mov_b32_e32 v62, v0
	v_mov_b32_e32 v63, v0
	v_mov_b32_e32 v64, v0
	v_mov_b32_e32 v65, v0
	v_mov_b32_e32 v66, v0
	v_mov_b32_e32 v67, v0
	v_mov_b32_e32 v68, v0
	v_mov_b32_e32 v69, v0
	v_mov_b32_e32 v70, v0
	v_mov_b32_e32 v71, v0
	v_mov_b32_e32 v80, v0
	v_mov_b32_e32 v81, v0
	v_mov_b32_e32 v82, v0
	v_mov_b32_e32 v83, v0
	v_mov_b32_e32 v84, v0
	v_mov_b32_e32 v85, v0
	v_mov_b32_e32 v86, v0
	v_mov_b32_e32 v87, v0
	v_mov_b32_e32 v96, v0
	v_mov_b32_e32 v97, v0
	v_mov_b32_e32 v98, v0
	v_mov_b32_e32 v99, v0
	v_mov_b32_e32 v100, v0
	v_mov_b32_e32 v101, v0
	v_mov_b32_e32 v102, v0
	v_mov_b32_e32 v103, v0
	v_mov_b32_e32 v116, v0
	v_mov_b32_e32 v117, v0
	v_mov_b32_e32 v118, v0
	v_mov_b32_e32 v119, v0
	v_mov_b32_e32 v128, v0
	v_mov_b32_e32 v129, v0
	v_mov_b32_e32 v130, v0
	v_mov_b32_e32 v131, v0
	v_mov_b32_e32 v72, v0
	v_mov_b32_e32 v73, v0
	v_mov_b32_e32 v74, v0
	v_mov_b32_e32 v75, v0
	v_mov_b32_e32 v76, v0
	v_mov_b32_e32 v77, v0
	v_mov_b32_e32 v78, v0
	v_mov_b32_e32 v79, v0
	v_mov_b32_e32 v88, v0
	v_mov_b32_e32 v89, v0
	v_mov_b32_e32 v90, v0
	v_mov_b32_e32 v91, v0
	v_mov_b32_e32 v92, v0
	v_mov_b32_e32 v93, v0
	v_mov_b32_e32 v94, v0
	v_mov_b32_e32 v95, v0
	v_mov_b32_e32 v104, v0
	v_mov_b32_e32 v105, v0
	v_mov_b32_e32 v106, v0
	v_mov_b32_e32 v107, v0
	v_mov_b32_e32 v108, v0
	v_mov_b32_e32 v109, v0
	v_mov_b32_e32 v110, v0
	v_mov_b32_e32 v111, v0
	v_mov_b32_e32 v120, v0
	v_mov_b32_e32 v121, v0
	v_mov_b32_e32 v122, v0
	v_mov_b32_e32 v123, v0
	v_mov_b32_e32 v132, v0
	v_mov_b32_e32 v133, v0
	v_mov_b32_e32 v134, v0
	v_mov_b32_e32 v135, v0
	s_cmp_eq_u32 s40, 1
	s_cbranch_scc1 .Lsb3
	s_andn2_b64 vcc, exec, s[4:5]
	s_cbranch_vccnz .Lsb3
	s_barrier

; #define PG8_BAR __builtin_amdgcn_s_barrier()
;     __device__ __forceinline__ void operator()(f32x4 (&acc)[2][2][4][2], const Unit& u, int wr, int wc, int fr, int fq, const LAS float*) const {
;     ...
;             slot[(size_t)(u.pn * 4 + wc) * MT + row0 + k * HALF + fq * 16] = v; }
; template <class Epi, bool KREV = false>
; __device__ __forceinline__ void gemm_phase(LAS unsigned char* lds, const Gemm g, const StaticOrder& S, const Epi& E, int wave_s) {
;     ...
;         if (!has_next) break;
; #pragma unroll
;         for (int a = 0; a < 2; ++a)
; #pragma unroll
;             for (int b = 0; b < 2; ++b)
; #pragma unroll
;                 for (int m = 0; m < 4; ++m)
; #pragma unroll
;                     for (int n = 0; n < 2; ++n) acc[a][b][m][n] = (f32x4){0.f, 0.f, 0.f, 0.f};
;         cur = nxt; cA = nA; cB = nB; ++ui;
;         if (wr == 1) PG8_BAR;
.LBB0_1050:
	s_or_b64 exec, exec, s[16:17]
	s_andn2_b64 vcc, exec, s[14:15]
	s_mov_b64 s[14:15], -1
	global_store_dword v[0:1], v4, off offset:512
	s_cbranch_vccnz .LBB0_1019
	s_andn2_b64 vcc, exec, s[4:5]
	s_cbranch_vccnz .LBB0_1018
	s_branch .LBB0_1018
